# all GEMMs: next tile's first B1/A fragment LDS reads issued at the start of the current tile's epilogue (first tile: from the phase prologue)
# speedup vs baseline: 1.0039x; 1.0039x over previous
; #define PG8_STAGE(bufoff, gbase, voff) do { _Pragma("unroll") for (int _i = 0; _i < 2; ++_i) \
;         __builtin_amdgcn_global_load_lds((const unsigned*)((const char*)(gbase) + (voff)[_i]), (PG8_LAS unsigned*)(lds + (bufoff) + ldsw + _i * 8192), 16, 0, 0); } while (0)
; #define PG8_LDA(dst, b, h) do { _Pragma("unroll") for (int m = 0; m < 4; ++m) _Pragma("unroll") for (int k = 0; k < 2; ++k) dst[m][k] = *(const PG8_LAS bf16x8*)(lds + PG8_SA(b, h) + aoff + m * 2048 + k * 1024); } while (0)
; #define PG8_LDB(dst, b, h) do { _Pragma("unroll") for (int n = 0; n < 2; ++n) _Pragma("unroll") for (int k = 0; k < 2; ++k) dst[n][k] = *(const PG8_LAS bf16x8*)(lds + PG8_SB(b, h) + boff + n * 2048 + k * 1024); } while (0)
; #define PG8_WAIT_V(n) asm volatile("s_waitcnt vmcnt(" #n ")" ::: "memory")
; #define PG8_BAR __builtin_amdgcn_s_barrier()
; #define PG8_SCHED __builtin_amdgcn_sched_barrier(0)
; template <class Epi, class Sched, bool ALIGN_EPI = false, bool SP2 = false>
; __device__ __forceinline__ void gemm_phase(PG8_LAS unsigned char* lds, const Gemm g, const Sched& S, const Epi& E) {
;     ...
;     const unsigned ldsw = (unsigned)wid * 1024u;
;     const int aoff = lds_byte(wr * 64 + fr, fq * 8), boff = lds_byte(wc * 32 + fr, fq * 8);
;     ...
;     Unit cur, nxt; int ui = 0;
;     if (!S.next(0, cur)) return;
;     f32x4 acc[2][2][4][2];
; #pragma unroll
;     for (int a = 0; a < 2; ++a)
; #pragma unroll
;         for (int b = 0; b < 2; ++b)
; #pragma unroll
;             for (int m = 0; m < 4; ++m)
; #pragma unroll
;                 for (int n = 0; n < 2; ++n) acc[a][b][m][n] = (f32x4){0.f, 0.f, 0.f, 0.f};
;     bf16x8 At[4][2], B0[2][2], B1[2][2];
;     const char* cA = (const char*)g.A + (size_t)cur.pm * tstep; const char* cB = (const char*)g.Bt + (size_t)cur.pn * tstep;
;     S.a_ready(cur);
;     if constexpr (SP2) {
;         PG8_STAGE(PG8_SB(0, 0), cB, voffB); PG8_STAGE(PG8_SB(0, 1), cB + hstep, voffB); PG8_STAGE(PG8_SA(0, 0), cA, voffA); PG8_STAGE(PG8_SA(0, 1), cA + hstep, voffA);
;         if (wr == 1) PG8_BAR;
;         PG8_WAIT_V(2); PG8_BAR;
;         PG8_STAGE(PG8_SB(1, 0), cB + kstep, voffB); PG8_STAGE(PG8_SB(1, 1), cB + hstep + kstep, voffB);
;         PG8_WAIT_V(4); PG8_BAR;
;     ...
;             PG8_LDB(B0, 0, 0); PG8_LDB(B1, 0, 1); PG8_SCHED; PG8_LDA(At, 0, 0); PG8_STAGE(PG8_SA(1, 0), a1, voffA); PG8_STAGE(PG8_SA(1, 1), a1 + hstep, voffA);
.LBB0_202:
	s_add_u32 s94, s36, 0x19000000
	s_addc_u32 s95, s37, 0
	s_lshl_b32 s6, s6, 5
	s_and_b32 s17, s6, 0x60
	s_add_i32 m0, s97, 0x18000
	v_lshl_add_u64 v[0:1], v[0:1], 0, s[26:27]
	s_lshl_b32 s16, s5, 13
	s_lshl_b32 s34, s17, 7
	s_waitcnt vmcnt(2)
	s_barrier
	global_load_lds_dwordx4 v[0:1], off
	s_add_i32 m0, s97, 0x1a000
	s_add_u32 s6, s10, 0x80080
	v_lshl_add_u64 v[0:1], v[2:3], 0, s[26:27]
	s_addc_u32 s7, s11, 0
	global_load_lds_dwordx4 v[0:1], off
	s_add_i32 m0, s97, 0x1c000
	v_lshl_add_u64 v[0:1], s[6:7], 0, v[204:205]
	global_load_lds_dwordx4 v[0:1], off
	v_lshl_add_u64 v[0:1], s[6:7], 0, v[128:129]
	s_add_i32 m0, s97, 0x1e000
	s_cmpk_lt_u32 s4, 0x100
	global_load_lds_dwordx4 v[0:1], off
	v_lshrrev_b32_e32 v1, 1, v5
	v_and_b32_e32 v1, 24, v1
	v_and_b32_e32 v0, 15, v5
	v_lshlrev_b32_e32 v2, 1, v1
	v_lshl_or_b32 v146, s5, 6, v0
	v_lshl_or_b32 v0, v0, 6, v2
	v_lshlrev_b32_e32 v2, 2, v5
	v_and_b32_e32 v2, 32, v2
	v_bitop3_b32 v3, v0, s16, v2 bitop3:0xde
	v_bitop3_b32 v147, v0, s34, v2 bitop3:0xde
	v_lshlrev_b32_e32 v0, 15, v9
	v_and_b32_e32 v0, 0xffff0000, v0
	v_or_b32_e32 v148, s17, v1
	v_lshl_add_u32 v0, v8, 12, v0
	v_and_b32_e32 v1, 1, v9
	v_lshl_or_b32 v0, v1, 6, v0
	v_lshl_add_u32 v134, v10, 1, v0
	v_lshlrev_b32_e32 v0, 15, v4
	v_and_b32_e32 v0, 0xffff0000, v0
	s_waitcnt vmcnt(4)
	v_lshl_add_u32 v0, v6, 12, v0
	v_and_b32_e32 v1, 1, v4
	v_lshl_or_b32 v0, v1, 6, v0
	v_readlane_b32 s4, v254, 61
	v_mov_b32_e32 v133, v205
	v_mov_b32_e32 v131, v205
	s_cselect_b64 s[76:77], -1, 0
	v_mov_b32_e32 v135, v205
	v_lshl_add_u32 v136, v7, 1, v0
	v_mov_b32_e32 v137, v205
	s_mov_b32 s84, 0
	v_add_u32_e32 v149, 0, v3
	v_readlane_b32 s34, v254, 54
	s_mov_b32 s35, s4
	s_barrier
	v_readlane_b32 s5, v254, 62
	v_add_u32_e32 v174, 0x14000, v147
	ds_read_b128 v[162:165], v174
	ds_read_b128 v[166:169], v174 offset:1024
	ds_read_b128 v[170:173], v174 offset:2048
	ds_read_b128 v[174:177], v174 offset:3072
	ds_read_b128 v[178:181], v149
	ds_read_b128 v[182:185], v149 offset:1024
	ds_read_b128 v[186:189], v149 offset:2048
	ds_read_b128 v[190:193], v149 offset:3072
	ds_read_b128 v[194:197], v149 offset:4096
	ds_read_b128 v[198:201], v149 offset:5120
	ds_read_b128 v[218:221], v149 offset:6144
	ds_read_b128 v[232:235], v149 offset:7168
	s_branch .LBB0_205

; #define PG8_STAGE(bufoff, gbase, voff) do { _Pragma("unroll") for (int _i = 0; _i < 2; ++_i) \
;         __builtin_amdgcn_global_load_lds((const unsigned*)((const char*)(gbase) + (voff)[_i]), (PG8_LAS unsigned*)(lds + (bufoff) + ldsw + _i * 8192), 16, 0, 0); } while (0)
; #define PG8_LDA(dst, b, h) do { _Pragma("unroll") for (int m = 0; m < 4; ++m) _Pragma("unroll") for (int k = 0; k < 2; ++k) dst[m][k] = *(const PG8_LAS bf16x8*)(lds + PG8_SA(b, h) + aoff + m * 2048 + k * 1024); } while (0)
; #define PG8_LDB(dst, b, h) do { _Pragma("unroll") for (int n = 0; n < 2; ++n) _Pragma("unroll") for (int k = 0; k < 2; ++k) dst[n][k] = *(const PG8_LAS bf16x8*)(lds + PG8_SB(b, h) + boff + n * 2048 + k * 1024); } while (0)
; #define PG8_WAIT_V(n) asm volatile("s_waitcnt vmcnt(" #n ")" ::: "memory")
; #define PG8_WAIT_L(n) asm volatile("s_waitcnt lgkmcnt(" #n ")" ::: "memory")
; #define PG8_BAR __builtin_amdgcn_s_barrier()
; #define PG8_SCHED __builtin_amdgcn_sched_barrier(0)
;     __device__ __forceinline__ void operator()(const f32x4 (&acc)[2][2][4][2], const Unit& u, int wr, int wc, int fr, int fq) const {
;     ...
;                 float rsc = sc; if (rsmode == 1) { const float r_ = rs[row0 + ai * HALF + m * 16]; rsc = sc * (ACT == 2 ? r_ * r_ : r_); }
; template <class Epi, class Sched, bool ALIGN_EPI = false, bool SP2 = false>
; __device__ __forceinline__ void gemm_phase(PG8_LAS unsigned char* lds, const Gemm g, const Sched& S, const Epi& E) {
;     ...
;         const bool has_next = S.next(ui + 1, nxt);
;         const char* nA = has_next ? (const char*)g.A + (size_t)nxt.pm * tstep : cA; const char* nB = has_next ? (const char*)g.Bt + (size_t)nxt.pn * tstep : cB;
;         for (int t = 0; t < nt; t += 2) {
;             const bool last = (t == nt - 2);
;             const char* a1 = cA + (size_t)(t + 1) * kstep;
;             const char* a2 = last ? nA : cA + (size_t)(t + 2) * kstep; const char* b2 = last ? nB : cB + (size_t)(t + 2) * kstep;
;             const char* a3 = a2 + kstep; const char* b3 = b2 + kstep;
;             if (last && has_next) S.a_ready(nxt);
;             if constexpr (SP2) {
;             PG8_LDB(B0, 0, 0); PG8_LDB(B1, 0, 1); PG8_SCHED; PG8_LDA(At, 0, 0); PG8_STAGE(PG8_SA(1, 0), a1, voffA); PG8_STAGE(PG8_SA(1, 1), a1 + hstep, voffA);
;             PG8_WAIT_V(8); PG8_WAIT_L(0); PG8_BAR; PG8_MMA(0, 0, At, B0); PG8_MMA(0, 1, At, B1); PG8_BAR; PG8_SCHED;
.LBB0_211:
	s_ashr_i32 s89, s88, 31
	s_lshl_b64 s[4:5], s[88:89], 20
	s_add_u32 s4, s22, s4
	s_addc_u32 s5, s75, s5
	s_and_b64 s[6:7], s[38:39], exec
	s_cselect_b32 s89, s5, s9
	s_cselect_b32 vcc_lo, s4, s8
	s_ashr_i32 s73, s72, 31
	s_lshl_b64 s[6:7], s[72:73], 20
	s_add_u32 s6, s68, s6
	s_addc_u32 s7, s69, s7
	s_and_b64 s[16:17], s[38:39], exec
	s_cselect_b32 s70, s7, s11
	s_cselect_b32 s71, s6, s10
	s_add_u32 s73, s10, 0x100
	s_addc_u32 vcc_hi, s11, 0
	s_mov_b32 s52, -2
	s_mov_b64 s[10:11], 0
	v_lshl_add_u64 v[138:139], s[8:9], 0, v[134:135]
	v_lshl_add_u64 v[140:141], s[8:9], 0, v[136:137]
	v_lshl_add_u32 v240, s35, 8, v146
	v_ashrrev_i32_e32 v241, 31, v240
	v_lshl_add_u64 v[240:241], v[240:241], 2, s[42:43]
	global_load_dword v242, v[240:241], off
	global_load_dword v243, v[240:241], off offset:64
	global_load_dword v244, v[240:241], off offset:128
	global_load_dword v245, v[240:241], off offset:192
	global_load_dword v246, v[240:241], off offset:512
	global_load_dword v247, v[240:241], off offset:576
	global_load_dword v248, v[240:241], off offset:640
	global_load_dword v249, v[240:241], off offset:704
	s_add_u32 s16, s8, s10
	s_addc_u32 s17, s9, s11
	s_add_u32 s44, s16, 0x100
	s_addc_u32 s45, s17, 0
	s_add_u32 s16, s73, s10
	s_addc_u32 s17, vcc_hi, s11
	s_add_i32 s53, 0, 0x10000
	s_cmpk_eq_i32 s10, 0xf00
	s_cselect_b32 s17, s70, s17
	s_cselect_b32 s16, s71, s16
	s_cselect_b32 s45, s89, s45
	s_cselect_b32 s44, vcc_lo, s44
	s_add_i32 s92, 0, 0x14000
	v_add_u32_e32 v158, s53, v147
	ds_read_b128 v[142:145], v158
	ds_read_b128 v[150:153], v158 offset:1024
	ds_read_b128 v[154:157], v158 offset:2048
	ds_read_b128 v[158:161], v158 offset:3072
	v_lshl_add_u64 v[202:203], v[138:139], 0, s[10:11]
	v_lshl_add_u64 v[206:207], v[202:203], 0, s[26:27]
	s_add_i32 m0, s97, 0x8000
	global_load_lds_dwordx4 v[206:207], off
	v_lshl_add_u64 v[206:207], v[140:141], 0, s[10:11]
	v_lshl_add_u64 v[208:209], v[206:207], 0, s[26:27]
	s_add_i32 m0, s97, 0xa000
	v_lshl_add_u64 v[202:203], v[202:203], 0, s[28:29]
	global_load_lds_dwordx4 v[208:209], off
	s_add_i32 m0, s97, 0xc000
	s_nop 0
	global_load_lds_dwordx4 v[202:203], off
	v_lshl_add_u64 v[202:203], v[206:207], 0, s[28:29]
	s_add_i32 m0, s97, 0xe000
	s_nop 0
	global_load_lds_dwordx4 v[202:203], off
	s_waitcnt vmcnt(8)
	s_waitcnt lgkmcnt(0)
	s_barrier
	v_mfma_f32_16x16x32_bf16 v[124:127], v[142:145], v[178:181], 0
	v_mfma_f32_16x16x32_bf16 v[120:123], v[154:157], v[178:181], 0
	v_mfma_f32_16x16x32_bf16 v[108:111], v[142:145], v[186:189], 0
	v_mfma_f32_16x16x32_bf16 v[104:107], v[154:157], v[186:189], 0
	v_mfma_f32_16x16x32_bf16 v[92:95], v[142:145], v[194:197], 0
	v_mfma_f32_16x16x32_bf16 v[88:91], v[154:157], v[194:197], 0
	v_mfma_f32_16x16x32_bf16 v[76:79], v[142:145], v[218:221], 0
	v_mfma_f32_16x16x32_bf16 v[72:75], v[154:157], v[218:221], 0
	v_mfma_f32_16x16x32_bf16 v[124:127], v[150:153], v[182:185], v[124:127]
	v_mfma_f32_16x16x32_bf16 v[120:123], v[158:161], v[182:185], v[120:123]
	v_mfma_f32_16x16x32_bf16 v[108:111], v[150:153], v[190:193], v[108:111]
	v_mfma_f32_16x16x32_bf16 v[104:107], v[158:161], v[190:193], v[104:107]
	v_mfma_f32_16x16x32_bf16 v[92:95], v[150:153], v[198:201], v[92:95]
	v_mfma_f32_16x16x32_bf16 v[88:91], v[158:161], v[198:201], v[88:91]
	v_mfma_f32_16x16x32_bf16 v[76:79], v[150:153], v[232:235], v[76:79]
	v_mfma_f32_16x16x32_bf16 v[72:75], v[158:161], v[232:235], v[72:75]
	v_mfma_f32_16x16x32_bf16 v[116:119], v[162:165], v[178:181], 0
	v_mfma_f32_16x16x32_bf16 v[112:115], v[170:173], v[178:181], 0
	v_mfma_f32_16x16x32_bf16 v[100:103], v[162:165], v[186:189], 0
	v_mfma_f32_16x16x32_bf16 v[96:99], v[170:173], v[186:189], 0
	v_mfma_f32_16x16x32_bf16 v[84:87], v[162:165], v[194:197], 0
	v_mfma_f32_16x16x32_bf16 v[80:83], v[170:173], v[194:197], 0
	v_mfma_f32_16x16x32_bf16 v[68:71], v[162:165], v[218:221], 0
	v_mfma_f32_16x16x32_bf16 v[64:67], v[170:173], v[218:221], 0
	v_mfma_f32_16x16x32_bf16 v[116:119], v[166:169], v[182:185], v[116:119]
	v_mfma_f32_16x16x32_bf16 v[112:115], v[174:177], v[182:185], v[112:115]
	v_mfma_f32_16x16x32_bf16 v[100:103], v[166:169], v[190:193], v[100:103]
	v_mfma_f32_16x16x32_bf16 v[96:99], v[174:177], v[190:193], v[96:99]
	v_mfma_f32_16x16x32_bf16 v[84:87], v[166:169], v[198:201], v[84:87]
	v_mfma_f32_16x16x32_bf16 v[80:83], v[174:177], v[198:201], v[80:83]
	v_mfma_f32_16x16x32_bf16 v[68:71], v[166:169], v[232:235], v[68:71]
	v_mfma_f32_16x16x32_bf16 v[64:67], v[174:177], v[232:235], v[64:67]
	s_barrier
; #define PG8_STAGE(bufoff, gbase, voff) do { _Pragma("unroll") for (int _i = 0; _i < 2; ++_i) \
;         __builtin_amdgcn_global_load_lds((const unsigned*)((const char*)(gbase) + (voff)[_i]), (PG8_LAS unsigned*)(lds + (bufoff) + ldsw + _i * 8192), 16, 0, 0); } while (0)
; #define PG8_LDA(dst, b, h) do { _Pragma("unroll") for (int m = 0; m < 4; ++m) _Pragma("unroll") for (int k = 0; k < 2; ++k) dst[m][k] = *(const PG8_LAS bf16x8*)(lds + PG8_SA(b, h) + aoff + m * 2048 + k * 1024); } while (0)
; #define PG8_MMA(ai, bj, At, Bt) do { __builtin_amdgcn_s_setprio(1); _Pragma("unroll") for (int m = 0; m < 4; ++m) _Pragma("unroll") for (int n = 0; n < 2; ++n) _Pragma("unroll") for (int k = 0; k < 2; ++k) \
;         acc[ai][bj][m][n] = __builtin_amdgcn_mfma_f32_16x16x32_bf16(Bt[n][k], At[m][k], acc[ai][bj][m][n], 0, 0, 0); __builtin_amdgcn_s_setprio(0); } while (0)
; #define PG8_WAIT_V(n) asm volatile("s_waitcnt vmcnt(" #n ")" ::: "memory")
; #define PG8_WAIT_L(n) asm volatile("s_waitcnt lgkmcnt(" #n ")" ::: "memory")
; #define PG8_BAR __builtin_amdgcn_s_barrier()
; #define PG8_SCHED __builtin_amdgcn_sched_barrier(0)
; template <class Epi, class Sched, bool ALIGN_EPI = false, bool SP2 = false>
; __device__ __forceinline__ void gemm_phase(PG8_LAS unsigned char* lds, const Gemm g, const Sched& S, const Epi& E) {
;     ...
;             PG8_LDA(At, 0, 1); PG8_STAGE(PG8_SB(0, 0), b2, voffB); PG8_STAGE(PG8_SB(0, 1), b2 + hstep, voffB);
;             PG8_WAIT_V(6); PG8_WAIT_L(0); PG8_BAR; PG8_MMA(1, 0, At, B0); PG8_MMA(1, 1, At, B1); PG8_BAR; PG8_SCHED;
	s_add_i32 s53, s53, s23
	v_lshl_add_u64 v[202:203], s[16:17], 0, v[204:205]
	s_mov_b32 m0, s53
	ds_read_b128 v[178:181], v149 offset:16384
	ds_read_b128 v[182:185], v149 offset:17408
	ds_read_b128 v[186:189], v149 offset:18432
	ds_read_b128 v[190:193], v149 offset:19456
	ds_read_b128 v[194:197], v149 offset:20480
	ds_read_b128 v[198:201], v149 offset:21504
	ds_read_b128 v[218:221], v149 offset:22528
	ds_read_b128 v[232:235], v149 offset:23552
	global_load_lds_dwordx4 v[202:203], off
	s_add_i32 m0, s53, 0x2000
	s_add_u32 s78, s16, 0x80000
	v_lshl_add_u64 v[206:207], s[16:17], 0, v[128:129]
	s_addc_u32 s79, s17, 0
	s_add_i32 s53, s92, s23
	global_load_lds_dwordx4 v[206:207], off
	v_lshl_add_u64 v[208:209], s[78:79], 0, v[204:205]
	s_mov_b32 m0, s53
	s_nop 0
	global_load_lds_dwordx4 v[208:209], off
	v_lshl_add_u64 v[208:209], s[78:79], 0, v[128:129]
	s_add_i32 m0, s53, 0x2000
	s_nop 0
	global_load_lds_dwordx4 v[208:209], off
	s_waitcnt vmcnt(6)
	s_waitcnt lgkmcnt(0)
	s_barrier
	v_mfma_f32_16x16x32_bf16 v[60:63], v[142:145], v[178:181], 0
	v_mfma_f32_16x16x32_bf16 v[56:59], v[154:157], v[178:181], 0
	v_mfma_f32_16x16x32_bf16 v[44:47], v[142:145], v[186:189], 0
	v_mfma_f32_16x16x32_bf16 v[40:43], v[154:157], v[186:189], 0
	v_mfma_f32_16x16x32_bf16 v[28:31], v[142:145], v[194:197], 0
	v_mfma_f32_16x16x32_bf16 v[24:27], v[154:157], v[194:197], 0
	v_mfma_f32_16x16x32_bf16 v[12:15], v[142:145], v[218:221], 0
	v_mfma_f32_16x16x32_bf16 v[8:11], v[154:157], v[218:221], 0
	v_mfma_f32_16x16x32_bf16 v[60:63], v[150:153], v[182:185], v[60:63]
	v_mfma_f32_16x16x32_bf16 v[56:59], v[158:161], v[182:185], v[56:59]
	v_mfma_f32_16x16x32_bf16 v[44:47], v[150:153], v[190:193], v[44:47]
	v_mfma_f32_16x16x32_bf16 v[40:43], v[158:161], v[190:193], v[40:43]
	v_mfma_f32_16x16x32_bf16 v[28:31], v[150:153], v[198:201], v[28:31]
	v_mfma_f32_16x16x32_bf16 v[24:27], v[158:161], v[198:201], v[24:27]
	v_mfma_f32_16x16x32_bf16 v[12:15], v[150:153], v[232:235], v[12:15]
	v_mfma_f32_16x16x32_bf16 v[8:11], v[158:161], v[232:235], v[8:11]
	v_mfma_f32_16x16x32_bf16 v[52:55], v[162:165], v[178:181], 0
	v_mfma_f32_16x16x32_bf16 v[48:51], v[170:173], v[178:181], 0
	v_mfma_f32_16x16x32_bf16 v[36:39], v[162:165], v[186:189], 0
	v_mfma_f32_16x16x32_bf16 v[32:35], v[170:173], v[186:189], 0
	v_mfma_f32_16x16x32_bf16 v[20:23], v[162:165], v[194:197], 0
	v_mfma_f32_16x16x32_bf16 v[16:19], v[170:173], v[194:197], 0
	v_mfma_f32_16x16x32_bf16 v[4:7], v[162:165], v[218:221], 0
	v_mfma_f32_16x16x32_bf16 v[0:3], v[170:173], v[218:221], 0
	v_mfma_f32_16x16x32_bf16 v[52:55], v[166:169], v[182:185], v[52:55]
	v_mfma_f32_16x16x32_bf16 v[48:51], v[174:177], v[182:185], v[48:51]
	v_mfma_f32_16x16x32_bf16 v[36:39], v[166:169], v[190:193], v[36:39]
	v_mfma_f32_16x16x32_bf16 v[32:35], v[174:177], v[190:193], v[32:35]
	v_mfma_f32_16x16x32_bf16 v[20:23], v[166:169], v[198:201], v[20:23]
	v_mfma_f32_16x16x32_bf16 v[16:19], v[174:177], v[198:201], v[16:19]
	v_mfma_f32_16x16x32_bf16 v[4:7], v[166:169], v[232:235], v[4:7]
	v_mfma_f32_16x16x32_bf16 v[0:3], v[174:177], v[232:235], v[0:3]
	s_barrier
	s_branch .Lpl_qk

; __device__ __forceinline__ unsigned cvt_pk_bf16(float lo, float hi) { unsigned r; asm volatile("v_cvt_pk_bf16_f32 %0, %1, %2" : "=v"(r) : "v"(lo), "v"(hi)); return r; }
; #define PG8_STAGE(bufoff, gbase, voff) do { _Pragma("unroll") for (int _i = 0; _i < 2; ++_i) \
;         __builtin_amdgcn_global_load_lds((const unsigned*)((const char*)(gbase) + (voff)[_i]), (PG8_LAS unsigned*)(lds + (bufoff) + ldsw + _i * 8192), 16, 0, 0); } while (0)
;     __device__ __forceinline__ void operator()(const f32x4 (&acc)[2][2][4][2], const Unit& u, int wr, int wc, int fr, int fq) const {
;         const int row0 = u.pm * BM + wr * 64 + fr; const int colt = u.pn * BM;
;         const float sc = (colt < scale_cols) ? scale0 : 1.f;
;         const int col0 = colt + wc * 32 + 8 * fq;
;         f32x4 cs[2][2];
; #pragma unroll
;         for (int bj = 0; bj < 2; ++bj) { cs[bj][0] = (f32x4){1.f, 1.f, 1.f, 1.f}; cs[bj][1] = cs[bj][0]; if (rsmode == 2) { cs[bj][0] = *(const f32x4*)(rs + col0 + bj * HALF); cs[bj][1] = *(const f32x4*)(rs + col0 + bj * HALF + 4); } }
; #pragma unroll
;         for (int ai = 0; ai < 2; ++ai)
; #pragma unroll
;             for (int m = 0; m < 4; ++m) { bf16_t* rowp = O + (size_t)(row0 + ai * HALF + m * 16) * ldc + col0;
;                 float rsc = sc; if (rsmode == 1) { const float r_ = rs[row0 + ai * HALF + m * 16]; rsc = sc * (ACT == 2 ? r_ * r_ : r_); }
; #pragma unroll
;                 for (int bj = 0; bj < 2; ++bj) { f32x4 v0 = acc[ai][bj][m][0], v1 = acc[ai][bj][m][1];
;                     if (ACT == 2) {
; #pragma unroll
;                         for (int e = 0; e < 4; ++e) { const float a0 = fmaxf(v0[e], 0.f), a1 = fmaxf(v1[e], 0.f); v0[e] = a0 * a0; v1[e] = a1 * a1; } }
;                     v0 = v0 * cs[bj][0] * rsc; v1 = v1 * cs[bj][1] * rsc; u32x4 w; w.x = cvt_pk_bf16(v0[0], v0[1]); w.y = cvt_pk_bf16(v0[2], v0[3]); w.z = cvt_pk_bf16(v1[0], v1[1]); w.w = cvt_pk_bf16(v1[2], v1[3]);
;                     *(u32x4*)(rowp + bj * HALF) = w; } }
; template <class Epi, class Sched, bool ALIGN_EPI = false, bool SP2 = false>
; __device__ __forceinline__ void gemm_phase(PG8_LAS unsigned char* lds, const Gemm g, const Sched& S, const Epi& E) {
;     ...
;             PG8_LDB(B0, 0, 0); PG8_LDB(B1, 0, 1); PG8_SCHED; PG8_LDA(At, 0, 0); PG8_STAGE(PG8_SA(1, 0), a1, voffA); PG8_STAGE(PG8_SA(1, 1), a1 + hstep, voffA);
.LBB0_215:
	v_add_u32_e32 v174, 0x14000, v147
	ds_read_b128 v[162:165], v174
	ds_read_b128 v[166:169], v174 offset:1024
	ds_read_b128 v[170:173], v174 offset:2048
	ds_read_b128 v[174:177], v174 offset:3072
	ds_read_b128 v[178:181], v149
	ds_read_b128 v[182:185], v149 offset:1024
	ds_read_b128 v[186:189], v149 offset:2048
	ds_read_b128 v[190:193], v149 offset:3072
	ds_read_b128 v[194:197], v149 offset:4096
	ds_read_b128 v[198:201], v149 offset:5120
	ds_read_b128 v[218:221], v149 offset:6144
	ds_read_b128 v[232:235], v149 offset:7168
	v_lshl_add_u32 v142, s35, 8, v146
	v_lshl_or_b32 v138, s34, 8, v148
	v_ashrrev_i32_e32 v143, 31, v142
	v_ashrrev_i32_e32 v139, 31, v138
	v_lshlrev_b64 v[140:141], 13, v[142:143]
	v_lshl_add_u64 v[140:141], s[94:95], 0, v[140:141]
	v_lshlrev_b64 v[144:145], 1, v[138:139]
	v_lshl_add_u64 v[138:139], v[140:141], 0, v[144:145]
	v_lshl_add_u64 v[140:141], v[142:143], 2, s[42:43]
	s_nop 0
	s_cmp_lt_i32 s34, 8
	s_cselect_b64 vcc, -1, 0
	v_cndmask_b32_e32 v150, 1.0, v228, vcc
	s_mov_b32 s8, 0x100000
	v_mul_f32_e32 v152, v150, v242
	v_pk_mul_f32 v[126:127], v[126:127], v[152:153] op_sel_hi:[1,0]
	v_pk_mul_f32 v[124:125], v[124:125], v[152:153] op_sel_hi:[1,0]
	v_pk_mul_f32 v[154:155], v[122:123], v[152:153] op_sel_hi:[1,0]
	v_pk_mul_f32 v[122:123], v[120:121], v[152:153] op_sel_hi:[1,0]
	v_cvt_pk_bf16_f32 v120, v124, v125
	v_cvt_pk_bf16_f32 v121, v126, v127
	v_pk_mul_f32 v[116:117], v[116:117], v[152:153] op_sel_hi:[1,0]
	v_cvt_pk_bf16_f32 v122, v122, v123
	v_cvt_pk_bf16_f32 v123, v154, v155
	global_store_dwordx4 v[138:139], v[120:123], off
	v_pk_mul_f32 v[118:119], v[118:119], v[152:153] op_sel_hi:[1,0]
	s_nop 0
	v_pk_mul_f32 v[120:121], v[114:115], v[152:153] op_sel_hi:[1,0]
	v_pk_mul_f32 v[114:115], v[112:113], v[152:153] op_sel_hi:[1,0]
	v_cvt_pk_bf16_f32 v112, v116, v117
	v_cvt_pk_bf16_f32 v113, v118, v119
	s_nop 0
	v_cvt_pk_bf16_f32 v114, v114, v115
	v_cvt_pk_bf16_f32 v115, v120, v121
	global_store_dwordx4 v[138:139], v[112:115], off offset:256
	s_nop 1
	v_or_b32_e32 v112, 16, v142
	v_ashrrev_i32_e32 v113, 31, v112
	v_lshlrev_b64 v[114:115], 13, v[112:113]
	v_lshl_add_u64 v[112:113], v[112:113], 2, s[42:43]
	s_nop 0
	v_lshl_add_u64 v[114:115], s[94:95], 0, v[114:115]
	v_lshl_add_u64 v[114:115], v[114:115], 0, v[144:145]
	v_mul_f32_e32 v112, v150, v243
	v_pk_mul_f32 v[110:111], v[110:111], v[112:113] op_sel_hi:[1,0]
	v_pk_mul_f32 v[108:109], v[108:109], v[112:113] op_sel_hi:[1,0]
	v_pk_mul_f32 v[116:117], v[106:107], v[112:113] op_sel_hi:[1,0]
	v_pk_mul_f32 v[106:107], v[104:105], v[112:113] op_sel_hi:[1,0]
	v_cvt_pk_bf16_f32 v104, v108, v109
	v_cvt_pk_bf16_f32 v105, v110, v111
	v_pk_mul_f32 v[100:101], v[100:101], v[112:113] op_sel_hi:[1,0]
	v_cvt_pk_bf16_f32 v106, v106, v107
	v_cvt_pk_bf16_f32 v107, v116, v117
	global_store_dwordx4 v[114:115], v[104:107], off
	v_pk_mul_f32 v[102:103], v[102:103], v[112:113] op_sel_hi:[1,0]
	s_nop 0
	v_pk_mul_f32 v[104:105], v[98:99], v[112:113] op_sel_hi:[1,0]
	v_pk_mul_f32 v[98:99], v[96:97], v[112:113] op_sel_hi:[1,0]
	v_cvt_pk_bf16_f32 v96, v100, v101
	v_cvt_pk_bf16_f32 v97, v102, v103
	s_nop 0
	v_cvt_pk_bf16_f32 v98, v98, v99
	v_cvt_pk_bf16_f32 v99, v104, v105
	global_store_dwordx4 v[114:115], v[96:99], off offset:256
	s_nop 1
	v_or_b32_e32 v96, 32, v142
	v_ashrrev_i32_e32 v97, 31, v96
	v_lshlrev_b64 v[98:99], 13, v[96:97]
	v_lshl_add_u64 v[96:97], v[96:97], 2, s[42:43]
	s_nop 0
	v_lshl_add_u64 v[98:99], s[94:95], 0, v[98:99]
	v_lshl_add_u64 v[98:99], v[98:99], 0, v[144:145]
	v_mul_f32_e32 v96, v150, v244
	v_pk_mul_f32 v[94:95], v[94:95], v[96:97] op_sel_hi:[1,0]
	v_pk_mul_f32 v[92:93], v[92:93], v[96:97] op_sel_hi:[1,0]
	v_pk_mul_f32 v[100:101], v[90:91], v[96:97] op_sel_hi:[1,0]
	v_pk_mul_f32 v[90:91], v[88:89], v[96:97] op_sel_hi:[1,0]
	v_cvt_pk_bf16_f32 v88, v92, v93
	v_cvt_pk_bf16_f32 v89, v94, v95
	v_pk_mul_f32 v[84:85], v[84:85], v[96:97] op_sel_hi:[1,0]
	v_cvt_pk_bf16_f32 v90, v90, v91
	v_cvt_pk_bf16_f32 v91, v100, v101
	global_store_dwordx4 v[98:99], v[88:91], off
	v_pk_mul_f32 v[86:87], v[86:87], v[96:97] op_sel_hi:[1,0]
	s_nop 0
	v_pk_mul_f32 v[88:89], v[82:83], v[96:97] op_sel_hi:[1,0]
	v_pk_mul_f32 v[82:83], v[80:81], v[96:97] op_sel_hi:[1,0]
	v_cvt_pk_bf16_f32 v80, v84, v85
	v_cvt_pk_bf16_f32 v81, v86, v87
	s_nop 0
	v_cvt_pk_bf16_f32 v82, v82, v83
	v_cvt_pk_bf16_f32 v83, v88, v89
	global_store_dwordx4 v[98:99], v[80:83], off offset:256
	s_nop 1
	v_or_b32_e32 v80, 48, v142
	v_ashrrev_i32_e32 v81, 31, v80
	v_lshlrev_b64 v[82:83], 13, v[80:81]
	v_lshl_add_u64 v[80:81], v[80:81], 2, s[42:43]
	s_nop 0
	v_lshl_add_u64 v[82:83], s[94:95], 0, v[82:83]
	v_lshl_add_u64 v[82:83], v[82:83], 0, v[144:145]
	v_mul_f32_e32 v80, v150, v245
	v_pk_mul_f32 v[78:79], v[78:79], v[80:81] op_sel_hi:[1,0]
	v_pk_mul_f32 v[76:77], v[76:77], v[80:81] op_sel_hi:[1,0]
	v_pk_mul_f32 v[84:85], v[74:75], v[80:81] op_sel_hi:[1,0]
	v_pk_mul_f32 v[74:75], v[72:73], v[80:81] op_sel_hi:[1,0]
	v_cvt_pk_bf16_f32 v72, v76, v77
; __device__ __forceinline__ unsigned cvt_pk_bf16(float lo, float hi) { unsigned r; asm volatile("v_cvt_pk_bf16_f32 %0, %1, %2" : "=v"(r) : "v"(lo), "v"(hi)); return r; }
; #define PG8_BAR __builtin_amdgcn_s_barrier()
;     __device__ __forceinline__ void operator()(const f32x4 (&acc)[2][2][4][2], const Unit& u, int wr, int wc, int fr, int fq) const {
;     ...
;             for (int m = 0; m < 4; ++m) { bf16_t* rowp = O + (size_t)(row0 + ai * HALF + m * 16) * ldc + col0;
;                 float rsc = sc; if (rsmode == 1) { const float r_ = rs[row0 + ai * HALF + m * 16]; rsc = sc * (ACT == 2 ? r_ * r_ : r_); }
; #pragma unroll
;                 for (int bj = 0; bj < 2; ++bj) { f32x4 v0 = acc[ai][bj][m][0], v1 = acc[ai][bj][m][1];
;                     if (ACT == 2) {
; #pragma unroll
;                         for (int e = 0; e < 4; ++e) { const float a0 = fmaxf(v0[e], 0.f), a1 = fmaxf(v1[e], 0.f); v0[e] = a0 * a0; v1[e] = a1 * a1; } }
;                     v0 = v0 * cs[bj][0] * rsc; v1 = v1 * cs[bj][1] * rsc; u32x4 w; w.x = cvt_pk_bf16(v0[0], v0[1]); w.y = cvt_pk_bf16(v0[2], v0[3]); w.z = cvt_pk_bf16(v1[0], v1[1]); w.w = cvt_pk_bf16(v1[2], v1[3]);
;                     *(u32x4*)(rowp + bj * HALF) = w; } }
; template <class Epi, class Sched, bool ALIGN_EPI = false, bool SP2 = false>
; __device__ __forceinline__ void gemm_phase(PG8_LAS unsigned char* lds, const Gemm g, const Sched& S, const Epi& E) {
;     ...
;         if constexpr (ALIGN_EPI) { if (wr == 0) PG8_BAR; }
;         if constexpr (!Epi::AFTER_DRAIN) { E(acc, cur, wr, wc, fr, fq); S.done(cur); }
;         if (!has_next) break;
; #pragma unroll
;         for (int a = 0; a < 2; ++a)
; #pragma unroll
;             for (int b = 0; b < 2; ++b)
; #pragma unroll
;                 for (int m = 0; m < 4; ++m)
; #pragma unroll
;                     for (int n = 0; n < 2; ++n) acc[a][b][m][n] = (f32x4){0.f, 0.f, 0.f, 0.f};
;         cur = nxt; cA = nA; cB = nB; ++ui;
;         if constexpr (ALIGN_EPI) { if (wr == 1) PG8_BAR; }
;     }
	v_cvt_pk_bf16_f32 v73, v78, v79
	v_pk_mul_f32 v[70:71], v[70:71], v[80:81] op_sel_hi:[1,0]
	v_cvt_pk_bf16_f32 v74, v74, v75
	v_cvt_pk_bf16_f32 v75, v84, v85
	global_store_dwordx4 v[82:83], v[72:75], off
	v_pk_mul_f32 v[68:69], v[68:69], v[80:81] op_sel_hi:[1,0]
	s_nop 0
	v_pk_mul_f32 v[72:73], v[66:67], v[80:81] op_sel_hi:[1,0]
	v_pk_mul_f32 v[66:67], v[64:65], v[80:81] op_sel_hi:[1,0]
	v_cvt_pk_bf16_f32 v64, v68, v69
	v_cvt_pk_bf16_f32 v65, v70, v71
	s_nop 0
	v_cvt_pk_bf16_f32 v66, v66, v67
	v_cvt_pk_bf16_f32 v67, v72, v73
	global_store_dwordx4 v[82:83], v[64:67], off offset:256
	s_nop 0
	s_nop 0
	v_lshl_add_u64 v[64:65], v[138:139], 0, s[30:31]
	v_mul_f32_e32 v66, v150, v246
	v_pk_mul_f32 v[60:61], v[60:61], v[66:67] op_sel_hi:[1,0]
	v_pk_mul_f32 v[68:69], v[58:59], v[66:67] op_sel_hi:[1,0]
	v_pk_mul_f32 v[58:59], v[56:57], v[66:67] op_sel_hi:[1,0]
	v_cvt_pk_bf16_f32 v56, v60, v61
	v_add_co_u32_e32 v60, vcc, s8, v138
	v_pk_mul_f32 v[62:63], v[62:63], v[66:67] op_sel_hi:[1,0]
	s_nop 0
	v_addc_co_u32_e32 v61, vcc, 0, v139, vcc
	v_cvt_pk_bf16_f32 v57, v62, v63
	v_cvt_pk_bf16_f32 v58, v58, v59
	v_cvt_pk_bf16_f32 v59, v68, v69
	global_store_dwordx4 v[60:61], v[56:59], off
	v_pk_mul_f32 v[54:55], v[54:55], v[66:67] op_sel_hi:[1,0]
	v_pk_mul_f32 v[52:53], v[52:53], v[66:67] op_sel_hi:[1,0]
	v_pk_mul_f32 v[56:57], v[50:51], v[66:67] op_sel_hi:[1,0]
	v_pk_mul_f32 v[50:51], v[48:49], v[66:67] op_sel_hi:[1,0]
	v_cvt_pk_bf16_f32 v48, v52, v53
	v_cvt_pk_bf16_f32 v49, v54, v55
	s_mov_b64 s[8:9], 0x120000
	v_cvt_pk_bf16_f32 v50, v50, v51
	v_cvt_pk_bf16_f32 v51, v56, v57
	global_store_dwordx4 v[64:65], v[48:51], off offset:256
	s_nop 0
	s_nop 0
	v_lshl_add_u64 v[48:49], v[138:139], 0, s[8:9]
	s_mov_b32 s8, 0x120000
	v_mul_f32_e32 v50, v150, v247
	v_pk_mul_f32 v[44:45], v[44:45], v[50:51] op_sel_hi:[1,0]
	v_pk_mul_f32 v[52:53], v[42:43], v[50:51] op_sel_hi:[1,0]
	v_pk_mul_f32 v[42:43], v[40:41], v[50:51] op_sel_hi:[1,0]
	v_cvt_pk_bf16_f32 v40, v44, v45
	v_add_co_u32_e32 v44, vcc, s8, v138
	v_pk_mul_f32 v[46:47], v[46:47], v[50:51] op_sel_hi:[1,0]
	s_nop 0
	v_addc_co_u32_e32 v45, vcc, 0, v139, vcc
	v_cvt_pk_bf16_f32 v41, v46, v47
	v_cvt_pk_bf16_f32 v42, v42, v43
	v_cvt_pk_bf16_f32 v43, v52, v53
	global_store_dwordx4 v[44:45], v[40:43], off
	v_pk_mul_f32 v[38:39], v[38:39], v[50:51] op_sel_hi:[1,0]
	v_pk_mul_f32 v[36:37], v[36:37], v[50:51] op_sel_hi:[1,0]
	v_pk_mul_f32 v[40:41], v[34:35], v[50:51] op_sel_hi:[1,0]
	v_pk_mul_f32 v[34:35], v[32:33], v[50:51] op_sel_hi:[1,0]
	v_cvt_pk_bf16_f32 v32, v36, v37
	v_cvt_pk_bf16_f32 v33, v38, v39
	s_mov_b64 s[8:9], 0x140000
	v_cvt_pk_bf16_f32 v34, v34, v35
	v_cvt_pk_bf16_f32 v35, v40, v41
	global_store_dwordx4 v[48:49], v[32:35], off offset:256
	s_nop 0
	s_nop 0
	v_lshl_add_u64 v[32:33], v[138:139], 0, s[8:9]
	s_mov_b32 s8, 0x140000
	v_mul_f32_e32 v34, v150, v248
	v_pk_mul_f32 v[28:29], v[28:29], v[34:35] op_sel_hi:[1,0]
	v_pk_mul_f32 v[36:37], v[26:27], v[34:35] op_sel_hi:[1,0]
	v_pk_mul_f32 v[26:27], v[24:25], v[34:35] op_sel_hi:[1,0]
	v_cvt_pk_bf16_f32 v24, v28, v29
	v_add_co_u32_e32 v28, vcc, s8, v138
	v_pk_mul_f32 v[30:31], v[30:31], v[34:35] op_sel_hi:[1,0]
	s_nop 0
	v_addc_co_u32_e32 v29, vcc, 0, v139, vcc
	v_cvt_pk_bf16_f32 v25, v30, v31
	v_cvt_pk_bf16_f32 v26, v26, v27
	v_cvt_pk_bf16_f32 v27, v36, v37
	global_store_dwordx4 v[28:29], v[24:27], off
	v_pk_mul_f32 v[22:23], v[22:23], v[34:35] op_sel_hi:[1,0]
	v_pk_mul_f32 v[20:21], v[20:21], v[34:35] op_sel_hi:[1,0]
	v_pk_mul_f32 v[24:25], v[18:19], v[34:35] op_sel_hi:[1,0]
	v_pk_mul_f32 v[18:19], v[16:17], v[34:35] op_sel_hi:[1,0]
	v_cvt_pk_bf16_f32 v16, v20, v21
	v_cvt_pk_bf16_f32 v17, v22, v23
	s_mov_b64 s[8:9], 0x160000
	v_cvt_pk_bf16_f32 v18, v18, v19
	v_cvt_pk_bf16_f32 v19, v24, v25
	global_store_dwordx4 v[32:33], v[16:19], off offset:256
	s_nop 0
	s_nop 0
	v_lshl_add_u64 v[18:19], v[138:139], 0, s[8:9]
	s_mov_b32 s8, 0x160000
	v_mul_f32_e32 v16, v150, v249
	v_pk_mul_f32 v[12:13], v[12:13], v[16:17] op_sel_hi:[1,0]
	v_pk_mul_f32 v[20:21], v[10:11], v[16:17] op_sel_hi:[1,0]
	v_pk_mul_f32 v[10:11], v[8:9], v[16:17] op_sel_hi:[1,0]
	v_cvt_pk_bf16_f32 v8, v12, v13
	v_add_co_u32_e32 v12, vcc, s8, v138
	v_pk_mul_f32 v[14:15], v[14:15], v[16:17] op_sel_hi:[1,0]
	s_nop 0
	v_addc_co_u32_e32 v13, vcc, 0, v139, vcc
	v_cvt_pk_bf16_f32 v9, v14, v15
	v_cvt_pk_bf16_f32 v10, v10, v11
	v_cvt_pk_bf16_f32 v11, v20, v21
	global_store_dwordx4 v[12:13], v[8:11], off
	s_mov_b64 s[8:9], -1
	s_andn2_b64 vcc, exec, s[38:39]
	v_pk_mul_f32 v[8:9], v[2:3], v[16:17] op_sel_hi:[1,0]
	v_pk_mul_f32 v[2:3], v[0:1], v[16:17] op_sel_hi:[1,0]
	v_pk_mul_f32 v[6:7], v[6:7], v[16:17] op_sel_hi:[1,0]
	v_pk_mul_f32 v[4:5], v[4:5], v[16:17] op_sel_hi:[1,0]
	s_nop 0
	v_cvt_pk_bf16_f32 v0, v4, v5
	v_cvt_pk_bf16_f32 v1, v6, v7
	v_cvt_pk_bf16_f32 v2, v2, v3
	v_cvt_pk_bf16_f32 v3, v8, v9
	global_store_dwordx4 v[18:19], v[0:3], off offset:256
	s_cbranch_vccnz .LBB0_204
	s_andn2_b64 vcc, exec, s[46:47]
	s_cbranch_vccnz .LBB0_203
	s_barrier
	s_branch .LBB0_203

; #define PG8_STAGE(bufoff, gbase, voff) do { _Pragma("unroll") for (int _i = 0; _i < 2; ++_i) \
;         __builtin_amdgcn_global_load_lds((const unsigned*)((const char*)(gbase) + (voff)[_i]), (PG8_LAS unsigned*)(lds + (bufoff) + ldsw + _i * 8192), 16, 0, 0); } while (0)
; #define PG8_LDA(dst, b, h) do { _Pragma("unroll") for (int m = 0; m < 4; ++m) _Pragma("unroll") for (int k = 0; k < 2; ++k) dst[m][k] = *(const PG8_LAS bf16x8*)(lds + PG8_SA(b, h) + aoff + m * 2048 + k * 1024); } while (0)
; #define PG8_LDB(dst, b, h) do { _Pragma("unroll") for (int n = 0; n < 2; ++n) _Pragma("unroll") for (int k = 0; k < 2; ++k) dst[n][k] = *(const PG8_LAS bf16x8*)(lds + PG8_SB(b, h) + boff + n * 2048 + k * 1024); } while (0)
; #define PG8_WAIT_V(n) asm volatile("s_waitcnt vmcnt(" #n ")" ::: "memory")
; #define PG8_BAR __builtin_amdgcn_s_barrier()
; #define PG8_SCHED __builtin_amdgcn_sched_barrier(0)
; template <class Epi, class Sched, bool ALIGN_EPI = false, bool SP2 = false>
; __device__ __forceinline__ void gemm_phase(PG8_LAS unsigned char* lds, const Gemm g, const Sched& S, const Epi& E) {
;     ...
;     const unsigned ldsw = (unsigned)wid * 1024u;
;     const int aoff = lds_byte(wr * 64 + fr, fq * 8), boff = lds_byte(wc * 32 + fr, fq * 8);
;     ...
;     Unit cur, nxt; int ui = 0;
;     if (!S.next(0, cur)) return;
;     f32x4 acc[2][2][4][2];
; #pragma unroll
;     for (int a = 0; a < 2; ++a)
; #pragma unroll
;         for (int b = 0; b < 2; ++b)
; #pragma unroll
;             for (int m = 0; m < 4; ++m)
; #pragma unroll
;                 for (int n = 0; n < 2; ++n) acc[a][b][m][n] = (f32x4){0.f, 0.f, 0.f, 0.f};
;     bf16x8 At[4][2], B0[2][2], B1[2][2];
;     const char* cA = (const char*)g.A + (size_t)cur.pm * tstep; const char* cB = (const char*)g.Bt + (size_t)cur.pn * tstep;
;     S.a_ready(cur);
;     if constexpr (SP2) {
;         PG8_STAGE(PG8_SB(0, 0), cB, voffB); PG8_STAGE(PG8_SB(0, 1), cB + hstep, voffB); PG8_STAGE(PG8_SA(0, 0), cA, voffA); PG8_STAGE(PG8_SA(0, 1), cA + hstep, voffA);
;         if (wr == 1) PG8_BAR;
;         PG8_WAIT_V(2); PG8_BAR;
;         PG8_STAGE(PG8_SB(1, 0), cB + kstep, voffB); PG8_STAGE(PG8_SB(1, 1), cB + hstep + kstep, voffB);
;         PG8_WAIT_V(4); PG8_BAR;
;     ...
;             PG8_LDB(B0, 0, 0); PG8_LDB(B1, 0, 1); PG8_SCHED; PG8_LDA(At, 0, 0); PG8_STAGE(PG8_SA(1, 0), a1, voffA); PG8_STAGE(PG8_SA(1, 1), a1 + hstep, voffA);
.LBB0_222:
	v_lshrrev_b32_e32 v12, 1, v10
	v_and_b32_e32 v12, 24, v12
	s_lshl_b32 s6, s6, 5
	v_and_b32_e32 v11, 15, v10
	v_lshlrev_b32_e32 v13, 1, v12
	v_lshlrev_b32_e32 v10, 2, v10
	s_and_b32 s35, s6, 0x60
	v_lshl_or_b32 v160, s7, 6, v11
	v_lshl_or_b32 v11, v11, 6, v13
	s_lshl_b32 s7, s7, 13
	v_and_b32_e32 v10, 32, v10
	s_lshl_b32 s6, s35, 7
	v_bitop3_b32 v161, v11, s6, v10 bitop3:0xde
	s_add_u32 s6, s36, 0x21000000
	v_bitop3_b32 v13, v11, s7, v10 bitop3:0xde
	s_addc_u32 s7, s37, 0
	s_add_i32 m0, s57, 0x18000
	v_lshl_add_u64 v[0:1], v[0:1], 0, s[26:27]
	s_waitcnt vmcnt(2)
	s_barrier
	global_load_lds_dwordx4 v[0:1], off
	s_add_i32 m0, s57, 0x1a000
	s_add_u32 s10, s44, 0x80080
	v_lshl_add_u64 v[0:1], v[2:3], 0, s[26:27]
	s_addc_u32 s11, s45, 0
	global_load_lds_dwordx4 v[0:1], off
	s_add_i32 m0, s57, 0x1c000
	v_lshl_add_u64 v[0:1], s[10:11], 0, v[204:205]
	global_load_lds_dwordx4 v[0:1], off
	v_lshl_add_u64 v[0:1], s[10:11], 0, v[144:145]
	s_add_i32 m0, s57, 0x1e000
	s_cmpk_lt_u32 s8, 0x100
	global_load_lds_dwordx4 v[0:1], off
	v_lshlrev_b32_e32 v0, 15, v8
	v_and_b32_e32 v0, 0xffff0000, v0
	v_lshl_add_u32 v0, v7, 12, v0
	v_and_b32_e32 v1, 1, v8
	v_lshl_or_b32 v0, v1, 6, v0
	v_lshl_add_u32 v150, v9, 1, v0
	v_lshlrev_b32_e32 v0, 15, v4
	v_and_b32_e32 v0, 0xffff0000, v0
	s_waitcnt vmcnt(4)
	v_lshl_add_u32 v0, v5, 12, v0
	v_and_b32_e32 v1, 1, v4
	v_lshl_or_b32 v0, v1, 6, v0
	v_readlane_b32 s10, v255, 1
	v_mov_b32_e32 v149, v205
	v_mov_b32_e32 v147, v205
	s_cselect_b64 s[8:9], -1, 0
	v_or_b32_e32 v162, s35, v12
	v_mov_b32_e32 v151, v205
	v_lshl_add_u32 v152, v6, 1, v0
	v_mov_b32_e32 v153, v205
	s_mov_b32 s35, 0
	v_add_u32_e32 v163, 0, v13
	v_readlane_b32 s37, v254, 57
	s_mov_b32 s36, s10
	s_barrier
	v_readlane_b32 s11, v255, 2
	ds_read_b128 v[180:183], v163
	ds_read_b128 v[184:187], v163 offset:1024
	ds_read_b128 v[188:191], v163 offset:2048
	ds_read_b128 v[192:195], v163 offset:3072
	ds_read_b128 v[196:199], v163 offset:4096
	ds_read_b128 v[200:203], v163 offset:5120
	ds_read_b128 v[218:221], v163 offset:6144
	ds_read_b128 v[232:235], v163 offset:7168
	s_branch .LBB0_225

; #define PG8_STAGE(bufoff, gbase, voff) do { _Pragma("unroll") for (int _i = 0; _i < 2; ++_i) \
;         __builtin_amdgcn_global_load_lds((const unsigned*)((const char*)(gbase) + (voff)[_i]), (PG8_LAS unsigned*)(lds + (bufoff) + ldsw + _i * 8192), 16, 0, 0); } while (0)
; #define PG8_LDA(dst, b, h) do { _Pragma("unroll") for (int m = 0; m < 4; ++m) _Pragma("unroll") for (int k = 0; k < 2; ++k) dst[m][k] = *(const PG8_LAS bf16x8*)(lds + PG8_SA(b, h) + aoff + m * 2048 + k * 1024); } while (0)
; #define PG8_LDB(dst, b, h) do { _Pragma("unroll") for (int n = 0; n < 2; ++n) _Pragma("unroll") for (int k = 0; k < 2; ++k) dst[n][k] = *(const PG8_LAS bf16x8*)(lds + PG8_SB(b, h) + boff + n * 2048 + k * 1024); } while (0)
; #define PG8_MMA(ai, bj, At, Bt) do { __builtin_amdgcn_s_setprio(1); _Pragma("unroll") for (int m = 0; m < 4; ++m) _Pragma("unroll") for (int n = 0; n < 2; ++n) _Pragma("unroll") for (int k = 0; k < 2; ++k) \
;         acc[ai][bj][m][n] = __builtin_amdgcn_mfma_f32_16x16x32_bf16(Bt[n][k], At[m][k], acc[ai][bj][m][n], 0, 0, 0); __builtin_amdgcn_s_setprio(0); } while (0)
; #define PG8_WAIT_V(n) asm volatile("s_waitcnt vmcnt(" #n ")" ::: "memory")
; #define PG8_WAIT_L(n) asm volatile("s_waitcnt lgkmcnt(" #n ")" ::: "memory")
; template <class Epi, class Sched, bool ALIGN_EPI = false, bool SP2 = false>
; __device__ __forceinline__ void gemm_phase(PG8_LAS unsigned char* lds, const Gemm g, const Sched& S, const Epi& E) {
;     ...
;         const bool has_next = S.next(ui + 1, nxt);
;         const char* nA = has_next ? (const char*)g.A + (size_t)nxt.pm * tstep : cA; const char* nB = has_next ? (const char*)g.Bt + (size_t)nxt.pn * tstep : cB;
;         for (int t = 0; t < nt; t += 2) {
;             const bool last = (t == nt - 2);
;             const char* a1 = cA + (size_t)(t + 1) * kstep;
;             const char* a2 = last ? nA : cA + (size_t)(t + 2) * kstep; const char* b2 = last ? nB : cB + (size_t)(t + 2) * kstep;
;             const char* a3 = a2 + kstep; const char* b3 = b2 + kstep;
;             if (last && has_next) S.a_ready(nxt);
;             if constexpr (SP2) {
;             PG8_LDB(B0, 0, 0); PG8_LDB(B1, 0, 1); PG8_SCHED; PG8_LDA(At, 0, 0); PG8_STAGE(PG8_SA(1, 0), a1, voffA); PG8_STAGE(PG8_SA(1, 1), a1 + hstep, voffA);
;             PG8_WAIT_V(8); PG8_WAIT_L(0); PG8_BAR; PG8_MMA(0, 0, At, B0); PG8_MMA(0, 1, At, B1); PG8_BAR; PG8_SCHED;
.LBB0_231:
	s_ashr_i32 s47, s46, 31
	s_lshl_b64 s[52:53], s[46:47], 20
	s_add_u32 s72, s20, s52
	s_addc_u32 s73, s21, s53
	s_and_b64 s[52:53], s[38:39], exec
	s_cselect_b32 s47, s73, s17
	s_cselect_b32 s68, s72, s16
	s_ashr_i32 s11, s10, 31
	s_lshl_b64 s[52:53], s[10:11], 20
	s_add_u32 s76, s22, s52
	s_addc_u32 s77, s75, s53
	s_and_b64 s[52:53], s[38:39], exec
	s_cselect_b32 s11, s77, s45
	s_cselect_b32 s69, s76, s44
	s_add_u32 s70, s44, 0x100
	s_addc_u32 s71, s45, 0
	v_lshl_add_u64 v[96:97], s[16:17], 0, v[150:151]
	v_lshl_add_u64 v[98:99], s[16:17], 0, v[152:153]
	s_mov_b32 s52, -2
	s_mov_b64 s[88:89], 0
	s_add_u32 s44, s16, s88
	s_addc_u32 s45, s17, s89
	s_add_u32 s53, s44, 0x100
	s_addc_u32 s78, s45, 0
	s_add_u32 s44, s70, s88
	s_addc_u32 s45, s71, s89
	s_add_i32 s79, 0, 0x10000
	s_cmpk_eq_i32 s88, 0xf00
	s_cselect_b32 s45, s11, s45
	s_cselect_b32 s44, s69, s44
	s_cselect_b32 s95, s47, s78
	s_cselect_b32 s94, s68, s53
	s_add_i32 s53, 0, 0x14000
	v_add_u32_e32 v154, s79, v161
	v_add_u32_e32 v158, s53, v161
	ds_read_b128 v[100:103], v154
	ds_read_b128 v[104:107], v154 offset:1024
	ds_read_b128 v[108:111], v154 offset:2048
	ds_read_b128 v[154:157], v154 offset:3072
	ds_read_b128 v[164:167], v158
	ds_read_b128 v[168:171], v158 offset:1024
	ds_read_b128 v[172:175], v158 offset:2048
	ds_read_b128 v[176:179], v158 offset:3072
	v_lshl_add_u64 v[158:159], v[96:97], 0, s[88:89]
	v_lshl_add_u64 v[206:207], v[158:159], 0, s[26:27]
	s_add_i32 m0, s57, 0x8000
	global_load_lds_dwordx4 v[206:207], off
	v_lshl_add_u64 v[206:207], v[98:99], 0, s[88:89]
	v_lshl_add_u64 v[208:209], v[206:207], 0, s[26:27]
	s_add_i32 m0, s57, 0xa000
	v_lshl_add_u64 v[158:159], v[158:159], 0, s[28:29]
	global_load_lds_dwordx4 v[208:209], off
	s_add_i32 m0, s57, 0xc000
	s_nop 0
	global_load_lds_dwordx4 v[158:159], off
	v_lshl_add_u64 v[158:159], v[206:207], 0, s[28:29]
	s_add_i32 m0, s57, 0xe000
	s_nop 0
	global_load_lds_dwordx4 v[158:159], off
	s_waitcnt vmcnt(8)
	s_waitcnt lgkmcnt(0)
	s_barrier
	v_mfma_f32_16x16x32_bf16 v[140:143], v[100:103], v[180:183], 0
	v_mfma_f32_16x16x32_bf16 v[136:139], v[108:111], v[180:183], 0
	v_mfma_f32_16x16x32_bf16 v[124:127], v[100:103], v[188:191], 0
	v_mfma_f32_16x16x32_bf16 v[120:123], v[108:111], v[188:191], 0
	v_mfma_f32_16x16x32_bf16 v[92:95], v[100:103], v[196:199], 0
	v_mfma_f32_16x16x32_bf16 v[88:91], v[108:111], v[196:199], 0
	v_mfma_f32_16x16x32_bf16 v[76:79], v[100:103], v[218:221], 0
	v_mfma_f32_16x16x32_bf16 v[72:75], v[108:111], v[218:221], 0
	v_mfma_f32_16x16x32_bf16 v[140:143], v[104:107], v[184:187], v[140:143]
	v_mfma_f32_16x16x32_bf16 v[136:139], v[154:157], v[184:187], v[136:139]
	v_mfma_f32_16x16x32_bf16 v[124:127], v[104:107], v[192:195], v[124:127]
	v_mfma_f32_16x16x32_bf16 v[120:123], v[154:157], v[192:195], v[120:123]
	v_mfma_f32_16x16x32_bf16 v[92:95], v[104:107], v[200:203], v[92:95]
	v_mfma_f32_16x16x32_bf16 v[88:91], v[154:157], v[200:203], v[88:91]
	v_mfma_f32_16x16x32_bf16 v[76:79], v[104:107], v[232:235], v[76:79]
	v_mfma_f32_16x16x32_bf16 v[72:75], v[154:157], v[232:235], v[72:75]
	v_mfma_f32_16x16x32_bf16 v[132:135], v[164:167], v[180:183], 0
	v_mfma_f32_16x16x32_bf16 v[128:131], v[172:175], v[180:183], 0
	v_mfma_f32_16x16x32_bf16 v[116:119], v[164:167], v[188:191], 0
	v_mfma_f32_16x16x32_bf16 v[112:115], v[172:175], v[188:191], 0
	v_mfma_f32_16x16x32_bf16 v[84:87], v[164:167], v[196:199], 0
	v_mfma_f32_16x16x32_bf16 v[80:83], v[172:175], v[196:199], 0
	v_mfma_f32_16x16x32_bf16 v[68:71], v[164:167], v[218:221], 0
	v_mfma_f32_16x16x32_bf16 v[64:67], v[172:175], v[218:221], 0
	v_mfma_f32_16x16x32_bf16 v[132:135], v[168:171], v[184:187], v[132:135]
	v_mfma_f32_16x16x32_bf16 v[128:131], v[176:179], v[184:187], v[128:131]
	v_mfma_f32_16x16x32_bf16 v[116:119], v[168:171], v[192:195], v[116:119]
	v_mfma_f32_16x16x32_bf16 v[112:115], v[176:179], v[192:195], v[112:115]
	v_mfma_f32_16x16x32_bf16 v[84:87], v[168:171], v[200:203], v[84:87]
	v_mfma_f32_16x16x32_bf16 v[80:83], v[176:179], v[200:203], v[80:83]
	v_mfma_f32_16x16x32_bf16 v[68:71], v[168:171], v[232:235], v[68:71]
	v_mfma_f32_16x16x32_bf16 v[64:67], v[176:179], v[232:235], v[64:67]
	s_barrier
; #define PG8_STAGE(bufoff, gbase, voff) do { _Pragma("unroll") for (int _i = 0; _i < 2; ++_i) \
;         __builtin_amdgcn_global_load_lds((const unsigned*)((const char*)(gbase) + (voff)[_i]), (PG8_LAS unsigned*)(lds + (bufoff) + ldsw + _i * 8192), 16, 0, 0); } while (0)
; #define PG8_LDA(dst, b, h) do { _Pragma("unroll") for (int m = 0; m < 4; ++m) _Pragma("unroll") for (int k = 0; k < 2; ++k) dst[m][k] = *(const PG8_LAS bf16x8*)(lds + PG8_SA(b, h) + aoff + m * 2048 + k * 1024); } while (0)
; #define PG8_MMA(ai, bj, At, Bt) do { __builtin_amdgcn_s_setprio(1); _Pragma("unroll") for (int m = 0; m < 4; ++m) _Pragma("unroll") for (int n = 0; n < 2; ++n) _Pragma("unroll") for (int k = 0; k < 2; ++k) \
;         acc[ai][bj][m][n] = __builtin_amdgcn_mfma_f32_16x16x32_bf16(Bt[n][k], At[m][k], acc[ai][bj][m][n], 0, 0, 0); __builtin_amdgcn_s_setprio(0); } while (0)
; #define PG8_WAIT_V(n) asm volatile("s_waitcnt vmcnt(" #n ")" ::: "memory")
; #define PG8_WAIT_L(n) asm volatile("s_waitcnt lgkmcnt(" #n ")" ::: "memory")
; #define PG8_BAR __builtin_amdgcn_s_barrier()
; #define PG8_SCHED __builtin_amdgcn_sched_barrier(0)
; template <class Epi, class Sched, bool ALIGN_EPI = false, bool SP2 = false>
; __device__ __forceinline__ void gemm_phase(PG8_LAS unsigned char* lds, const Gemm g, const Sched& S, const Epi& E) {
;     ...
;             PG8_LDA(At, 0, 1); PG8_STAGE(PG8_SB(0, 0), b2, voffB); PG8_STAGE(PG8_SB(0, 1), b2 + hstep, voffB);
;             PG8_WAIT_V(6); PG8_WAIT_L(0); PG8_BAR; PG8_MMA(1, 0, At, B0); PG8_MMA(1, 1, At, B1); PG8_BAR; PG8_SCHED;
	s_add_i32 s78, s79, s23
	v_lshl_add_u64 v[158:159], s[44:45], 0, v[204:205]
	s_mov_b32 m0, s78
	ds_read_b128 v[180:183], v163 offset:16384
	ds_read_b128 v[184:187], v163 offset:17408
	ds_read_b128 v[188:191], v163 offset:18432
	ds_read_b128 v[192:195], v163 offset:19456
	ds_read_b128 v[196:199], v163 offset:20480
	ds_read_b128 v[200:203], v163 offset:21504
	ds_read_b128 v[218:221], v163 offset:22528
	ds_read_b128 v[232:235], v163 offset:23552
	global_load_lds_dwordx4 v[158:159], off
	s_add_i32 m0, s78, 0x2000
	s_add_u32 s78, s44, 0x80000
	v_lshl_add_u64 v[206:207], s[44:45], 0, v[144:145]
	s_addc_u32 s79, s45, 0
	s_add_i32 s53, s53, s23
	global_load_lds_dwordx4 v[206:207], off
	v_lshl_add_u64 v[208:209], s[78:79], 0, v[204:205]
	s_mov_b32 m0, s53
	s_nop 0
	global_load_lds_dwordx4 v[208:209], off
	v_lshl_add_u64 v[208:209], s[78:79], 0, v[144:145]
	s_add_i32 m0, s53, 0x2000
	s_nop 0
	global_load_lds_dwordx4 v[208:209], off
	s_waitcnt vmcnt(6)
	s_waitcnt lgkmcnt(0)
	s_barrier
	v_mfma_f32_16x16x32_bf16 v[60:63], v[100:103], v[180:183], 0
	v_mfma_f32_16x16x32_bf16 v[56:59], v[108:111], v[180:183], 0
	v_mfma_f32_16x16x32_bf16 v[48:51], v[100:103], v[188:191], 0
	v_mfma_f32_16x16x32_bf16 v[40:43], v[108:111], v[188:191], 0
	v_mfma_f32_16x16x32_bf16 v[32:35], v[100:103], v[196:199], 0
	v_mfma_f32_16x16x32_bf16 v[24:27], v[108:111], v[196:199], 0
	v_mfma_f32_16x16x32_bf16 v[16:19], v[100:103], v[218:221], 0
	v_mfma_f32_16x16x32_bf16 v[8:11], v[108:111], v[218:221], 0
	v_mfma_f32_16x16x32_bf16 v[60:63], v[104:107], v[184:187], v[60:63]
	v_mfma_f32_16x16x32_bf16 v[56:59], v[154:157], v[184:187], v[56:59]
	v_mfma_f32_16x16x32_bf16 v[48:51], v[104:107], v[192:195], v[48:51]
	v_mfma_f32_16x16x32_bf16 v[40:43], v[154:157], v[192:195], v[40:43]
	v_mfma_f32_16x16x32_bf16 v[32:35], v[104:107], v[200:203], v[32:35]
	v_mfma_f32_16x16x32_bf16 v[24:27], v[154:157], v[200:203], v[24:27]
	v_mfma_f32_16x16x32_bf16 v[16:19], v[104:107], v[232:235], v[16:19]
	v_mfma_f32_16x16x32_bf16 v[8:11], v[154:157], v[232:235], v[8:11]
	v_mfma_f32_16x16x32_bf16 v[52:55], v[164:167], v[180:183], 0
	v_mfma_f32_16x16x32_bf16 v[44:47], v[172:175], v[180:183], 0
	v_mfma_f32_16x16x32_bf16 v[36:39], v[164:167], v[188:191], 0
	v_mfma_f32_16x16x32_bf16 v[28:31], v[172:175], v[188:191], 0
	v_mfma_f32_16x16x32_bf16 v[20:23], v[164:167], v[196:199], 0
	v_mfma_f32_16x16x32_bf16 v[12:15], v[172:175], v[196:199], 0
	v_mfma_f32_16x16x32_bf16 v[4:7], v[164:167], v[218:221], 0
	v_mfma_f32_16x16x32_bf16 v[0:3], v[172:175], v[218:221], 0
	v_mfma_f32_16x16x32_bf16 v[52:55], v[168:171], v[184:187], v[52:55]
	v_mfma_f32_16x16x32_bf16 v[44:47], v[176:179], v[184:187], v[44:47]
	v_mfma_f32_16x16x32_bf16 v[36:39], v[168:171], v[192:195], v[36:39]
	v_mfma_f32_16x16x32_bf16 v[28:31], v[176:179], v[192:195], v[28:31]
	v_mfma_f32_16x16x32_bf16 v[20:23], v[168:171], v[200:203], v[20:23]
	v_mfma_f32_16x16x32_bf16 v[12:15], v[176:179], v[200:203], v[12:15]
	v_mfma_f32_16x16x32_bf16 v[4:7], v[168:171], v[232:235], v[4:7]
	v_mfma_f32_16x16x32_bf16 v[0:3], v[176:179], v[232:235], v[0:3]
	s_barrier
	s_branch .Lpl_vt

; __device__ __forceinline__ unsigned cvt_pk_bf16(float lo, float hi) { unsigned r; asm volatile("v_cvt_pk_bf16_f32 %0, %1, %2" : "=v"(r) : "v"(lo), "v"(hi)); return r; }
; #define PG8_STAGE(bufoff, gbase, voff) do { _Pragma("unroll") for (int _i = 0; _i < 2; ++_i) \
;         __builtin_amdgcn_global_load_lds((const unsigned*)((const char*)(gbase) + (voff)[_i]), (PG8_LAS unsigned*)(lds + (bufoff) + ldsw + _i * 8192), 16, 0, 0); } while (0)
;     __device__ __forceinline__ void operator()(const f32x4 (&acc)[2][2][4][2], const Unit& u, int wr, int wc, int fr, int fq) const {
;         const int row0 = u.pm * BM + wr * 64 + fr; const int colt = u.pn * BM;
;         const float sc = (colt < scale_cols) ? scale0 : 1.f;
;         const int col0 = colt + wc * 32 + 8 * fq;
;         f32x4 cs[2][2];
; #pragma unroll
;         for (int bj = 0; bj < 2; ++bj) { cs[bj][0] = (f32x4){1.f, 1.f, 1.f, 1.f}; cs[bj][1] = cs[bj][0]; if (rsmode == 2) { cs[bj][0] = *(const f32x4*)(rs + col0 + bj * HALF); cs[bj][1] = *(const f32x4*)(rs + col0 + bj * HALF + 4); } }
; #pragma unroll
;         for (int ai = 0; ai < 2; ++ai)
; #pragma unroll
;             for (int m = 0; m < 4; ++m) { bf16_t* rowp = O + (size_t)(row0 + ai * HALF + m * 16) * ldc + col0;
;                 float rsc = sc; if (rsmode == 1) { const float r_ = rs[row0 + ai * HALF + m * 16]; rsc = sc * (ACT == 2 ? r_ * r_ : r_); }
; #pragma unroll
;                 for (int bj = 0; bj < 2; ++bj) { f32x4 v0 = acc[ai][bj][m][0], v1 = acc[ai][bj][m][1];
;                     if (ACT == 2) {
; #pragma unroll
;                         for (int e = 0; e < 4; ++e) { const float a0 = fmaxf(v0[e], 0.f), a1 = fmaxf(v1[e], 0.f); v0[e] = a0 * a0; v1[e] = a1 * a1; } }
;                     v0 = v0 * cs[bj][0] * rsc; v1 = v1 * cs[bj][1] * rsc; u32x4 w; w.x = cvt_pk_bf16(v0[0], v0[1]); w.y = cvt_pk_bf16(v0[2], v0[3]); w.z = cvt_pk_bf16(v1[0], v1[1]); w.w = cvt_pk_bf16(v1[2], v1[3]);
;                     *(u32x4*)(rowp + bj * HALF) = w; } }
; template <class Epi, class Sched, bool ALIGN_EPI = false, bool SP2 = false>
; __device__ __forceinline__ void gemm_phase(PG8_LAS unsigned char* lds, const Gemm g, const Sched& S, const Epi& E) {
;     ...
;             PG8_LDB(B0, 0, 0); PG8_LDB(B1, 0, 1); PG8_SCHED; PG8_LDA(At, 0, 0); PG8_STAGE(PG8_SA(1, 0), a1, voffA); PG8_STAGE(PG8_SA(1, 1), a1 + hstep, voffA);
.LBB0_235:
	ds_read_b128 v[180:183], v163
	ds_read_b128 v[184:187], v163 offset:1024
	ds_read_b128 v[188:191], v163 offset:2048
	ds_read_b128 v[192:195], v163 offset:3072
	ds_read_b128 v[196:199], v163 offset:4096
	ds_read_b128 v[200:203], v163 offset:5120
	ds_read_b128 v[218:221], v163 offset:6144
	ds_read_b128 v[232:235], v163 offset:7168
	v_lshl_or_b32 v154, s37, 8, v162
	v_ashrrev_i32_e32 v155, 31, v154
	v_lshl_add_u64 v[100:101], v[154:155], 2, s[42:43]
	global_load_dwordx4 v[104:107], v[100:101], off offset:16
	global_load_dwordx4 v[108:111], v[100:101], off
	global_load_dwordx4 v[96:99], v[100:101], off offset:528
	s_nop 0
	global_load_dwordx4 v[100:103], v[100:101], off offset:512
	v_lshl_add_u32 v158, s36, 8, v160
	v_ashrrev_i32_e32 v159, 31, v158
	v_lshlrev_b64 v[156:157], 15, v[158:159]
	v_lshl_add_u64 v[164:165], s[6:7], 0, v[156:157]
	v_lshlrev_b64 v[156:157], 1, v[154:155]
	v_lshl_add_u64 v[154:155], v[164:165], 0, v[156:157]
	s_mov_b32 s11, 0x400000
	s_mov_b64 s[16:17], 0x400000
	s_waitcnt vmcnt(0)
	v_pk_mul_f32 v[164:165], v[138:139], v[106:107]
	v_pk_mul_f32 v[142:143], v[142:143], v[110:111]
	v_pk_mul_f32 v[140:141], v[140:141], v[108:109]
	v_pk_mul_f32 v[138:139], v[136:137], v[104:105]
	v_cvt_pk_bf16_f32 v136, v140, v141
	v_cvt_pk_bf16_f32 v137, v142, v143
	v_pk_mul_f32 v[132:133], v[132:133], v[100:101]
	v_cvt_pk_bf16_f32 v138, v138, v139
	v_cvt_pk_bf16_f32 v139, v164, v165
	global_store_dwordx4 v[154:155], v[136:139], off
	v_pk_mul_f32 v[134:135], v[134:135], v[102:103]
	v_pk_mul_f32 v[126:127], v[126:127], v[110:111]
	v_pk_mul_f32 v[136:137], v[130:131], v[98:99]
	v_pk_mul_f32 v[130:131], v[128:129], v[96:97]
	v_cvt_pk_bf16_f32 v128, v132, v133
	v_cvt_pk_bf16_f32 v129, v134, v135
	v_pk_mul_f32 v[124:125], v[124:125], v[108:109]
	v_cvt_pk_bf16_f32 v130, v130, v131
	v_cvt_pk_bf16_f32 v131, v136, v137
	global_store_dwordx4 v[154:155], v[128:131], off offset:256
	v_pk_mul_f32 v[116:117], v[116:117], v[100:101]
	v_pk_mul_f32 v[118:119], v[118:119], v[102:103]
	v_or_b32_e32 v128, 16, v158
	v_ashrrev_i32_e32 v129, 31, v128
	v_lshlrev_b64 v[128:129], 15, v[128:129]
	v_lshl_add_u64 v[128:129], s[6:7], 0, v[128:129]
	v_lshl_add_u64 v[128:129], v[128:129], 0, v[156:157]
	v_pk_mul_f32 v[130:131], v[122:123], v[106:107]
	v_pk_mul_f32 v[122:123], v[120:121], v[104:105]
	v_cvt_pk_bf16_f32 v120, v124, v125
	v_cvt_pk_bf16_f32 v121, v126, v127
	v_pk_mul_f32 v[94:95], v[94:95], v[110:111]
	v_cvt_pk_bf16_f32 v122, v122, v123
	v_cvt_pk_bf16_f32 v123, v130, v131
	global_store_dwordx4 v[128:129], v[120:123], off
	v_pk_mul_f32 v[92:93], v[92:93], v[108:109]
	v_pk_mul_f32 v[84:85], v[84:85], v[100:101]
	v_pk_mul_f32 v[120:121], v[114:115], v[98:99]
	v_pk_mul_f32 v[114:115], v[112:113], v[96:97]
	v_cvt_pk_bf16_f32 v112, v116, v117
	v_cvt_pk_bf16_f32 v113, v118, v119
	v_pk_mul_f32 v[86:87], v[86:87], v[102:103]
	v_cvt_pk_bf16_f32 v114, v114, v115
	v_cvt_pk_bf16_f32 v115, v120, v121
	global_store_dwordx4 v[128:129], v[112:115], off offset:256
	v_pk_mul_f32 v[78:79], v[78:79], v[110:111]
	v_pk_mul_f32 v[76:77], v[76:77], v[108:109]
	v_or_b32_e32 v112, 32, v158
	v_ashrrev_i32_e32 v113, 31, v112
	v_lshlrev_b64 v[112:113], 15, v[112:113]
	v_lshl_add_u64 v[112:113], s[6:7], 0, v[112:113]
	v_lshl_add_u64 v[112:113], v[112:113], 0, v[156:157]
	v_pk_mul_f32 v[114:115], v[90:91], v[106:107]
	v_pk_mul_f32 v[90:91], v[88:89], v[104:105]
	v_cvt_pk_bf16_f32 v88, v92, v93
	v_cvt_pk_bf16_f32 v89, v94, v95
	v_pk_mul_f32 v[70:71], v[70:71], v[102:103]
	v_cvt_pk_bf16_f32 v90, v90, v91
	v_cvt_pk_bf16_f32 v91, v114, v115
	global_store_dwordx4 v[112:113], v[88:91], off
	v_pk_mul_f32 v[68:69], v[68:69], v[100:101]
	v_pk_mul_f32 v[60:61], v[60:61], v[108:109]
	v_pk_mul_f32 v[88:89], v[82:83], v[98:99]
	v_pk_mul_f32 v[82:83], v[80:81], v[96:97]
	v_cvt_pk_bf16_f32 v80, v84, v85
	v_cvt_pk_bf16_f32 v81, v86, v87
	v_pk_mul_f32 v[62:63], v[62:63], v[110:111]
	v_cvt_pk_bf16_f32 v82, v82, v83
	v_cvt_pk_bf16_f32 v83, v88, v89
	global_store_dwordx4 v[112:113], v[80:83], off offset:256
	v_pk_mul_f32 v[54:55], v[54:55], v[102:103]
	v_pk_mul_f32 v[52:53], v[52:53], v[100:101]
	v_or_b32_e32 v80, 48, v158
	v_ashrrev_i32_e32 v81, 31, v80
	v_lshlrev_b64 v[80:81], 15, v[80:81]
; __device__ __forceinline__ unsigned cvt_pk_bf16(float lo, float hi) { unsigned r; asm volatile("v_cvt_pk_bf16_f32 %0, %1, %2" : "=v"(r) : "v"(lo), "v"(hi)); return r; }
; #define PG8_BAR __builtin_amdgcn_s_barrier()
;     __device__ __forceinline__ void operator()(const f32x4 (&acc)[2][2][4][2], const Unit& u, int wr, int wc, int fr, int fq) const {
;     ...
;             for (int m = 0; m < 4; ++m) { bf16_t* rowp = O + (size_t)(row0 + ai * HALF + m * 16) * ldc + col0;
;                 float rsc = sc; if (rsmode == 1) { const float r_ = rs[row0 + ai * HALF + m * 16]; rsc = sc * (ACT == 2 ? r_ * r_ : r_); }
; #pragma unroll
;                 for (int bj = 0; bj < 2; ++bj) { f32x4 v0 = acc[ai][bj][m][0], v1 = acc[ai][bj][m][1];
;                     if (ACT == 2) {
; #pragma unroll
;                         for (int e = 0; e < 4; ++e) { const float a0 = fmaxf(v0[e], 0.f), a1 = fmaxf(v1[e], 0.f); v0[e] = a0 * a0; v1[e] = a1 * a1; } }
;                     v0 = v0 * cs[bj][0] * rsc; v1 = v1 * cs[bj][1] * rsc; u32x4 w; w.x = cvt_pk_bf16(v0[0], v0[1]); w.y = cvt_pk_bf16(v0[2], v0[3]); w.z = cvt_pk_bf16(v1[0], v1[1]); w.w = cvt_pk_bf16(v1[2], v1[3]);
;                     *(u32x4*)(rowp + bj * HALF) = w; } }
; template <class Epi, class Sched, bool ALIGN_EPI = false, bool SP2 = false>
; __device__ __forceinline__ void gemm_phase(PG8_LAS unsigned char* lds, const Gemm g, const Sched& S, const Epi& E) {
;     ...
;         if constexpr (ALIGN_EPI) { if (wr == 0) PG8_BAR; }
;         if constexpr (!Epi::AFTER_DRAIN) { E(acc, cur, wr, wc, fr, fq); S.done(cur); }
;         if (!has_next) break;
; #pragma unroll
;         for (int a = 0; a < 2; ++a)
; #pragma unroll
;             for (int b = 0; b < 2; ++b)
; #pragma unroll
;                 for (int m = 0; m < 4; ++m)
; #pragma unroll
;                     for (int n = 0; n < 2; ++n) acc[a][b][m][n] = (f32x4){0.f, 0.f, 0.f, 0.f};
;         cur = nxt; cA = nA; cB = nB; ++ui;
;         if constexpr (ALIGN_EPI) { if (wr == 1) PG8_BAR; }
;     }
	v_lshl_add_u64 v[80:81], s[6:7], 0, v[80:81]
	v_lshl_add_u64 v[80:81], v[80:81], 0, v[156:157]
	v_pk_mul_f32 v[82:83], v[74:75], v[106:107]
	v_pk_mul_f32 v[74:75], v[72:73], v[104:105]
	v_cvt_pk_bf16_f32 v72, v76, v77
	v_cvt_pk_bf16_f32 v73, v78, v79
	v_pk_mul_f32 v[48:49], v[48:49], v[108:109]
	v_cvt_pk_bf16_f32 v74, v74, v75
	v_cvt_pk_bf16_f32 v75, v82, v83
	global_store_dwordx4 v[80:81], v[72:75], off
	v_pk_mul_f32 v[38:39], v[38:39], v[102:103]
	v_pk_mul_f32 v[36:37], v[36:37], v[100:101]
	v_pk_mul_f32 v[72:73], v[66:67], v[98:99]
	v_pk_mul_f32 v[66:67], v[64:65], v[96:97]
	v_cvt_pk_bf16_f32 v64, v68, v69
	v_cvt_pk_bf16_f32 v65, v70, v71
	v_pk_mul_f32 v[32:33], v[32:33], v[108:109]
	v_cvt_pk_bf16_f32 v66, v66, v67
	v_cvt_pk_bf16_f32 v67, v72, v73
	global_store_dwordx4 v[80:81], v[64:67], off offset:256
	v_pk_mul_f32 v[22:23], v[22:23], v[102:103]
	v_pk_mul_f32 v[20:21], v[20:21], v[100:101]
	v_pk_mul_f32 v[66:67], v[58:59], v[106:107]
	v_pk_mul_f32 v[58:59], v[56:57], v[104:105]
	v_cvt_pk_bf16_f32 v56, v60, v61
	v_add_co_u32_e32 v60, vcc, s11, v154
	v_cvt_pk_bf16_f32 v57, v62, v63
	v_cvt_pk_bf16_f32 v58, v58, v59
	v_cvt_pk_bf16_f32 v59, v66, v67
	v_lshl_add_u64 v[64:65], v[154:155], 0, s[16:17]
	s_nop 0
	v_addc_co_u32_e32 v61, vcc, 0, v155, vcc
	global_store_dwordx4 v[60:61], v[56:59], off
	s_mov_b32 s11, 0x480000
	s_mov_b64 s[16:17], 0x480000
	v_pk_mul_f32 v[56:57], v[46:47], v[98:99]
	v_pk_mul_f32 v[46:47], v[44:45], v[96:97]
	v_cvt_pk_bf16_f32 v44, v52, v53
	v_cvt_pk_bf16_f32 v45, v54, v55
	v_pk_mul_f32 v[16:17], v[16:17], v[108:109]
	v_cvt_pk_bf16_f32 v46, v46, v47
	v_cvt_pk_bf16_f32 v47, v56, v57
	global_store_dwordx4 v[64:65], v[44:47], off offset:256
	v_pk_mul_f32 v[6:7], v[6:7], v[102:103]
	v_pk_mul_f32 v[4:5], v[4:5], v[100:101]
	v_pk_mul_f32 v[46:47], v[50:51], v[110:111]
	v_pk_mul_f32 v[50:51], v[42:43], v[106:107]
	v_pk_mul_f32 v[42:43], v[40:41], v[104:105]
	v_cvt_pk_bf16_f32 v40, v48, v49
	v_cvt_pk_bf16_f32 v41, v46, v47
	v_add_co_u32_e32 v46, vcc, s11, v154
	v_cvt_pk_bf16_f32 v42, v42, v43
	v_cvt_pk_bf16_f32 v43, v50, v51
	v_lshl_add_u64 v[44:45], v[154:155], 0, s[16:17]
	s_nop 0
	v_addc_co_u32_e32 v47, vcc, 0, v155, vcc
	global_store_dwordx4 v[46:47], v[40:43], off
	s_mov_b32 s11, 0x500000
	s_mov_b64 s[16:17], 0x500000
	v_pk_mul_f32 v[40:41], v[30:31], v[98:99]
	v_pk_mul_f32 v[30:31], v[28:29], v[96:97]
	v_cvt_pk_bf16_f32 v28, v36, v37
	v_cvt_pk_bf16_f32 v29, v38, v39
	s_nop 0
	v_cvt_pk_bf16_f32 v30, v30, v31
	v_cvt_pk_bf16_f32 v31, v40, v41
	global_store_dwordx4 v[44:45], v[28:31], off offset:256
	s_nop 1
	v_pk_mul_f32 v[30:31], v[34:35], v[110:111]
	v_pk_mul_f32 v[34:35], v[26:27], v[106:107]
	v_pk_mul_f32 v[26:27], v[24:25], v[104:105]
	v_cvt_pk_bf16_f32 v24, v32, v33
	v_cvt_pk_bf16_f32 v25, v30, v31
	v_add_co_u32_e32 v30, vcc, s11, v154
	v_cvt_pk_bf16_f32 v26, v26, v27
	v_cvt_pk_bf16_f32 v27, v34, v35
	v_lshl_add_u64 v[28:29], v[154:155], 0, s[16:17]
	s_nop 0
	v_addc_co_u32_e32 v31, vcc, 0, v155, vcc
	global_store_dwordx4 v[30:31], v[24:27], off
	s_mov_b32 s11, 0x580000
	s_mov_b64 s[16:17], 0x580000
	v_pk_mul_f32 v[24:25], v[14:15], v[98:99]
	v_pk_mul_f32 v[14:15], v[12:13], v[96:97]
	v_cvt_pk_bf16_f32 v12, v20, v21
	v_cvt_pk_bf16_f32 v13, v22, v23
	s_nop 0
	v_cvt_pk_bf16_f32 v14, v14, v15
	v_cvt_pk_bf16_f32 v15, v24, v25
	global_store_dwordx4 v[28:29], v[12:15], off offset:256
	s_nop 1
	v_pk_mul_f32 v[14:15], v[18:19], v[110:111]
	v_pk_mul_f32 v[18:19], v[10:11], v[106:107]
	v_pk_mul_f32 v[10:11], v[8:9], v[104:105]
	v_cvt_pk_bf16_f32 v8, v16, v17
	v_cvt_pk_bf16_f32 v9, v14, v15
	v_add_co_u32_e32 v14, vcc, s11, v154
	v_lshl_add_u64 v[12:13], v[154:155], 0, s[16:17]
	s_nop 0
	v_addc_co_u32_e32 v15, vcc, 0, v155, vcc
	v_cvt_pk_bf16_f32 v10, v10, v11
	v_cvt_pk_bf16_f32 v11, v18, v19
	global_store_dwordx4 v[14:15], v[8:11], off
	s_mov_b64 s[16:17], -1
	s_andn2_b64 vcc, exec, s[38:39]
	v_pk_mul_f32 v[8:9], v[2:3], v[98:99]
	v_pk_mul_f32 v[2:3], v[0:1], v[96:97]
	v_cvt_pk_bf16_f32 v0, v4, v5
	v_cvt_pk_bf16_f32 v1, v6, v7
	s_nop 0
	v_cvt_pk_bf16_f32 v2, v2, v3
	v_cvt_pk_bf16_f32 v3, v8, v9
	global_store_dwordx4 v[12:13], v[0:3], off offset:256
	s_cbranch_vccnz .LBB0_224
	s_andn2_b64 vcc, exec, s[4:5]
	s_cbranch_vccnz .LBB0_223
	s_barrier
	s_branch .LBB0_223

; #define PG8_STAGE(bufoff, gbase, voff) do { _Pragma("unroll") for (int _i = 0; _i < 2; ++_i) \
;         __builtin_amdgcn_global_load_lds((const unsigned*)((const char*)(gbase) + (voff)[_i]), (PG8_LAS unsigned*)(lds + (bufoff) + ldsw + _i * 8192), 16, 0, 0); } while (0)
; #define PG8_LDA(dst, b, h) do { _Pragma("unroll") for (int m = 0; m < 4; ++m) _Pragma("unroll") for (int k = 0; k < 2; ++k) dst[m][k] = *(const PG8_LAS bf16x8*)(lds + PG8_SA(b, h) + aoff + m * 2048 + k * 1024); } while (0)
; #define PG8_LDB(dst, b, h) do { _Pragma("unroll") for (int n = 0; n < 2; ++n) _Pragma("unroll") for (int k = 0; k < 2; ++k) dst[n][k] = *(const PG8_LAS bf16x8*)(lds + PG8_SB(b, h) + boff + n * 2048 + k * 1024); } while (0)
; #define PG8_WAIT_V(n) asm volatile("s_waitcnt vmcnt(" #n ")" ::: "memory")
; #define PG8_BAR __builtin_amdgcn_s_barrier()
; #define PG8_SCHED __builtin_amdgcn_sched_barrier(0)
; template <class Epi, class Sched, bool ALIGN_EPI = false, bool SP2 = false>
; __device__ __forceinline__ void gemm_phase(PG8_LAS unsigned char* lds, const Gemm g, const Sched& S, const Epi& E) {
;     ...
;     const unsigned ldsw = (unsigned)wid * 1024u;
;     const int aoff = lds_byte(wr * 64 + fr, fq * 8), boff = lds_byte(wc * 32 + fr, fq * 8);
;     ...
;     Unit cur, nxt; int ui = 0;
;     if (!S.next(0, cur)) return;
;     f32x4 acc[2][2][4][2];
; #pragma unroll
;     for (int a = 0; a < 2; ++a)
; #pragma unroll
;         for (int b = 0; b < 2; ++b)
; #pragma unroll
;             for (int m = 0; m < 4; ++m)
; #pragma unroll
;                 for (int n = 0; n < 2; ++n) acc[a][b][m][n] = (f32x4){0.f, 0.f, 0.f, 0.f};
;     bf16x8 At[4][2], B0[2][2], B1[2][2];
;     const char* cA = (const char*)g.A + (size_t)cur.pm * tstep; const char* cB = (const char*)g.Bt + (size_t)cur.pn * tstep;
;     S.a_ready(cur);
;     if constexpr (SP2) {
;         PG8_STAGE(PG8_SB(0, 0), cB, voffB); PG8_STAGE(PG8_SB(0, 1), cB + hstep, voffB); PG8_STAGE(PG8_SA(0, 0), cA, voffA); PG8_STAGE(PG8_SA(0, 1), cA + hstep, voffA);
;         if (wr == 1) PG8_BAR;
;         PG8_WAIT_V(2); PG8_BAR;
;         PG8_STAGE(PG8_SB(1, 0), cB + kstep, voffB); PG8_STAGE(PG8_SB(1, 1), cB + hstep + kstep, voffB);
;         PG8_WAIT_V(4); PG8_BAR;
;     ...
;             PG8_LDB(B0, 0, 0); PG8_LDB(B1, 0, 1); PG8_SCHED; PG8_LDA(At, 0, 0); PG8_STAGE(PG8_SA(1, 0), a1, voffA); PG8_STAGE(PG8_SA(1, 1), a1 + hstep, voffA);
.LBB0_416:
	s_add_u32 s8, s8, 0x35000000
	v_lshrrev_b32_e32 v12, 1, v10
	s_addc_u32 s9, s9, 0
	v_and_b32_e32 v12, 24, v12
	s_lshl_b32 s11, s11, 5
	v_and_b32_e32 v11, 15, v10
	v_lshlrev_b32_e32 v13, 1, v12
	v_lshlrev_b32_e32 v10, 2, v10
	s_and_b32 s37, s11, 0x60
	s_add_i32 m0, s23, 0x18000
	v_lshl_add_u64 v[0:1], v[0:1], 0, s[26:27]
	v_lshl_or_b32 v142, s16, 6, v11
	v_lshl_or_b32 v11, v11, 6, v13
	s_lshl_b32 s16, s16, 13
	v_and_b32_e32 v10, 32, v10
	s_lshl_b32 s11, s37, 7
	s_waitcnt vmcnt(2)
	s_barrier
	global_load_lds_dwordx4 v[0:1], off
	s_add_i32 m0, s23, 0x1a000
	v_bitop3_b32 v13, v11, s16, v10 bitop3:0xde
	s_add_u32 s16, s44, 0x80080
	v_lshl_add_u64 v[0:1], v[2:3], 0, s[26:27]
	s_addc_u32 s17, s45, 0
	global_load_lds_dwordx4 v[0:1], off
	s_add_i32 m0, s23, 0x1c000
	v_lshl_add_u64 v[0:1], s[16:17], 0, v[204:205]
	global_load_lds_dwordx4 v[0:1], off
	v_lshl_add_u64 v[0:1], s[16:17], 0, v[128:129]
	s_add_i32 m0, s23, 0x1e000
	v_readlane_b32 s16, v255, 20
	global_load_lds_dwordx4 v[0:1], off
	v_lshlrev_b32_e32 v0, 15, v8
	v_and_b32_e32 v0, 0xffff0000, v0
	v_lshl_add_u32 v0, v7, 12, v0
	v_and_b32_e32 v1, 1, v8
	v_lshl_or_b32 v0, v1, 6, v0
	v_lshl_add_u32 v134, v9, 1, v0
	v_lshlrev_b32_e32 v0, 15, v4
	v_and_b32_e32 v0, 0xffff0000, v0
	s_waitcnt vmcnt(4)
	v_lshl_add_u32 v0, v5, 12, v0
	v_and_b32_e32 v1, 1, v4
	v_readlane_b32 s17, v255, 21
	s_cmpk_lt_u32 s10, 0x100
	v_lshl_or_b32 v0, v1, 6, v0
	s_mov_b32 s57, s16
	v_readlane_b32 s16, v255, 7
	v_mov_b32_e32 v133, v205
	v_mov_b32_e32 v131, v205
	v_bitop3_b32 v143, v11, s11, v10 bitop3:0xde
	s_cselect_b64 s[10:11], -1, 0
	v_or_b32_e32 v144, s37, v12
	v_mov_b32_e32 v135, v205
	v_lshl_add_u32 v136, v6, 1, v0
	v_mov_b32_e32 v137, v205
	s_mov_b32 s37, 0
	v_add_u32_e32 v145, 0, v13
	v_readlane_b32 s75, v254, 60
	v_readlane_b32 s17, v255, 8
	s_barrier
	v_add_u32_e32 v174, 0x14000, v143
	ds_read_b128 v[162:165], v174
	ds_read_b128 v[166:169], v174 offset:1024
	ds_read_b128 v[170:173], v174 offset:2048
	ds_read_b128 v[174:177], v174 offset:3072
	ds_read_b128 v[178:181], v145
	ds_read_b128 v[182:185], v145 offset:1024
	ds_read_b128 v[186:189], v145 offset:2048
	ds_read_b128 v[190:193], v145 offset:3072
	ds_read_b128 v[194:197], v145 offset:4096
	ds_read_b128 v[198:201], v145 offset:5120
	ds_read_b128 v[206:209], v145 offset:6144
	ds_read_b128 v[218:221], v145 offset:7168
	s_branch .LBB0_419

; #define PG8_STAGE(bufoff, gbase, voff) do { _Pragma("unroll") for (int _i = 0; _i < 2; ++_i) \
;         __builtin_amdgcn_global_load_lds((const unsigned*)((const char*)(gbase) + (voff)[_i]), (PG8_LAS unsigned*)(lds + (bufoff) + ldsw + _i * 8192), 16, 0, 0); } while (0)
; #define PG8_LDA(dst, b, h) do { _Pragma("unroll") for (int m = 0; m < 4; ++m) _Pragma("unroll") for (int k = 0; k < 2; ++k) dst[m][k] = *(const PG8_LAS bf16x8*)(lds + PG8_SA(b, h) + aoff + m * 2048 + k * 1024); } while (0)
; #define PG8_LDB(dst, b, h) do { _Pragma("unroll") for (int n = 0; n < 2; ++n) _Pragma("unroll") for (int k = 0; k < 2; ++k) dst[n][k] = *(const PG8_LAS bf16x8*)(lds + PG8_SB(b, h) + boff + n * 2048 + k * 1024); } while (0)
; #define PG8_MMA(ai, bj, At, Bt) do { __builtin_amdgcn_s_setprio(1); _Pragma("unroll") for (int m = 0; m < 4; ++m) _Pragma("unroll") for (int n = 0; n < 2; ++n) _Pragma("unroll") for (int k = 0; k < 2; ++k) \
;         acc[ai][bj][m][n] = __builtin_amdgcn_mfma_f32_16x16x32_bf16(Bt[n][k], At[m][k], acc[ai][bj][m][n], 0, 0, 0); __builtin_amdgcn_s_setprio(0); } while (0)
; #define PG8_WAIT_V(n) asm volatile("s_waitcnt vmcnt(" #n ")" ::: "memory")
; #define PG8_WAIT_L(n) asm volatile("s_waitcnt lgkmcnt(" #n ")" ::: "memory")
; template <class Epi, class Sched, bool ALIGN_EPI = false, bool SP2 = false>
; __device__ __forceinline__ void gemm_phase(PG8_LAS unsigned char* lds, const Gemm g, const Sched& S, const Epi& E) {
;     ...
;         const bool has_next = S.next(ui + 1, nxt);
;         const char* nA = has_next ? (const char*)g.A + (size_t)nxt.pm * tstep : cA; const char* nB = has_next ? (const char*)g.Bt + (size_t)nxt.pn * tstep : cB;
;         for (int t = 0; t < nt; t += 2) {
;             const bool last = (t == nt - 2);
;             const char* a1 = cA + (size_t)(t + 1) * kstep;
;             const char* a2 = last ? nA : cA + (size_t)(t + 2) * kstep; const char* b2 = last ? nB : cB + (size_t)(t + 2) * kstep;
;             const char* a3 = a2 + kstep; const char* b3 = b2 + kstep;
;             if (last && has_next) S.a_ready(nxt);
;             if constexpr (SP2) {
;             PG8_LDB(B0, 0, 0); PG8_LDB(B1, 0, 1); PG8_SCHED; PG8_LDA(At, 0, 0); PG8_STAGE(PG8_SA(1, 0), a1, voffA); PG8_STAGE(PG8_SA(1, 1), a1 + hstep, voffA);
;             PG8_WAIT_V(8); PG8_WAIT_L(0); PG8_BAR; PG8_MMA(0, 0, At, B0); PG8_MMA(0, 1, At, B1); PG8_BAR; PG8_SCHED;
.LBB0_425:
	s_ashr_i32 s47, s46, 31
	s_lshl_b64 s[52:53], s[46:47], 20
	s_add_u32 s72, s98, s52
	s_addc_u32 s73, s99, s53
	s_and_b64 s[52:53], s[38:39], exec
	s_cselect_b32 s47, s73, s17
	s_cselect_b32 s68, s72, s16
	s_ashr_i32 s43, s42, 31
	s_lshl_b64 s[52:53], s[42:43], 20
	s_add_u32 s76, s20, s52
	s_addc_u32 s77, s21, s53
	s_and_b64 s[52:53], s[38:39], exec
	s_cselect_b32 s43, s77, s45
	s_cselect_b32 s69, s76, s44
	s_add_u32 s70, s44, 0x100
	s_addc_u32 s71, s45, 0
	v_lshl_add_u64 v[138:139], s[16:17], 0, v[134:135]
	v_lshl_add_u64 v[140:141], s[16:17], 0, v[136:137]
	s_mov_b32 s52, -2
	s_mov_b64 s[88:89], 0
	s_add_u32 s44, s16, s88
	s_addc_u32 s45, s17, s89
	s_add_u32 s53, s44, 0x100
	s_addc_u32 s78, s45, 0
	s_add_u32 s44, s70, s88
	s_addc_u32 s45, s71, s89
	s_add_i32 s79, 0, 0x10000
	s_cmpk_eq_i32 s88, 0xf00
	s_cselect_b32 s45, s43, s45
	s_cselect_b32 s44, s69, s44
	s_cselect_b32 s95, s47, s78
	s_cselect_b32 s94, s68, s53
	s_add_i32 s53, 0, 0x14000
	v_add_u32_e32 v158, s79, v143
	ds_read_b128 v[146:149], v158
	ds_read_b128 v[150:153], v158 offset:1024
	ds_read_b128 v[154:157], v158 offset:2048
	ds_read_b128 v[158:161], v158 offset:3072
	v_lshl_add_u64 v[202:203], v[138:139], 0, s[88:89]
	v_lshl_add_u64 v[222:223], v[202:203], 0, s[26:27]
	s_add_i32 m0, s23, 0x8000
	global_load_lds_dwordx4 v[222:223], off
	v_lshl_add_u64 v[222:223], v[140:141], 0, s[88:89]
	v_lshl_add_u64 v[232:233], v[222:223], 0, s[26:27]
	s_add_i32 m0, s23, 0xa000
	v_lshl_add_u64 v[202:203], v[202:203], 0, s[28:29]
	global_load_lds_dwordx4 v[232:233], off
	s_add_i32 m0, s23, 0xc000
	s_nop 0
	global_load_lds_dwordx4 v[202:203], off
	v_lshl_add_u64 v[202:203], v[222:223], 0, s[28:29]
	s_add_i32 m0, s23, 0xe000
	s_nop 0
	global_load_lds_dwordx4 v[202:203], off
	s_waitcnt vmcnt(8)
	s_waitcnt lgkmcnt(0)
	s_barrier
	v_mfma_f32_16x16x32_bf16 v[124:127], v[146:149], v[178:181], 0
	v_mfma_f32_16x16x32_bf16 v[120:123], v[154:157], v[178:181], 0
	v_mfma_f32_16x16x32_bf16 v[116:119], v[146:149], v[186:189], 0
	v_mfma_f32_16x16x32_bf16 v[108:111], v[154:157], v[186:189], 0
	v_mfma_f32_16x16x32_bf16 v[100:103], v[146:149], v[194:197], 0
	v_mfma_f32_16x16x32_bf16 v[92:95], v[154:157], v[194:197], 0
	v_mfma_f32_16x16x32_bf16 v[84:87], v[146:149], v[206:209], 0
	v_mfma_f32_16x16x32_bf16 v[76:79], v[154:157], v[206:209], 0
	v_mfma_f32_16x16x32_bf16 v[124:127], v[150:153], v[182:185], v[124:127]
	v_mfma_f32_16x16x32_bf16 v[120:123], v[158:161], v[182:185], v[120:123]
	v_mfma_f32_16x16x32_bf16 v[116:119], v[150:153], v[190:193], v[116:119]
	v_mfma_f32_16x16x32_bf16 v[108:111], v[158:161], v[190:193], v[108:111]
	v_mfma_f32_16x16x32_bf16 v[100:103], v[150:153], v[198:201], v[100:103]
	v_mfma_f32_16x16x32_bf16 v[92:95], v[158:161], v[198:201], v[92:95]
	v_mfma_f32_16x16x32_bf16 v[84:87], v[150:153], v[218:221], v[84:87]
	v_mfma_f32_16x16x32_bf16 v[76:79], v[158:161], v[218:221], v[76:79]
	v_mfma_f32_16x16x32_bf16 v[112:115], v[162:165], v[178:181], 0
	v_mfma_f32_16x16x32_bf16 v[104:107], v[170:173], v[178:181], 0
	v_mfma_f32_16x16x32_bf16 v[96:99], v[162:165], v[186:189], 0
	v_mfma_f32_16x16x32_bf16 v[88:91], v[170:173], v[186:189], 0
	v_mfma_f32_16x16x32_bf16 v[80:83], v[162:165], v[194:197], 0
	v_mfma_f32_16x16x32_bf16 v[72:75], v[170:173], v[194:197], 0
	v_mfma_f32_16x16x32_bf16 v[68:71], v[162:165], v[206:209], 0
	v_mfma_f32_16x16x32_bf16 v[64:67], v[170:173], v[206:209], 0
	v_mfma_f32_16x16x32_bf16 v[112:115], v[166:169], v[182:185], v[112:115]
	v_mfma_f32_16x16x32_bf16 v[104:107], v[174:177], v[182:185], v[104:107]
	v_mfma_f32_16x16x32_bf16 v[96:99], v[166:169], v[190:193], v[96:99]
	v_mfma_f32_16x16x32_bf16 v[88:91], v[174:177], v[190:193], v[88:91]
	v_mfma_f32_16x16x32_bf16 v[80:83], v[166:169], v[198:201], v[80:83]
	v_mfma_f32_16x16x32_bf16 v[72:75], v[174:177], v[198:201], v[72:75]
	v_mfma_f32_16x16x32_bf16 v[68:71], v[166:169], v[218:221], v[68:71]
	v_mfma_f32_16x16x32_bf16 v[64:67], v[174:177], v[218:221], v[64:67]
	s_barrier
; #define PG8_STAGE(bufoff, gbase, voff) do { _Pragma("unroll") for (int _i = 0; _i < 2; ++_i) \
;         __builtin_amdgcn_global_load_lds((const unsigned*)((const char*)(gbase) + (voff)[_i]), (PG8_LAS unsigned*)(lds + (bufoff) + ldsw + _i * 8192), 16, 0, 0); } while (0)
; #define PG8_LDA(dst, b, h) do { _Pragma("unroll") for (int m = 0; m < 4; ++m) _Pragma("unroll") for (int k = 0; k < 2; ++k) dst[m][k] = *(const PG8_LAS bf16x8*)(lds + PG8_SA(b, h) + aoff + m * 2048 + k * 1024); } while (0)
; #define PG8_MMA(ai, bj, At, Bt) do { __builtin_amdgcn_s_setprio(1); _Pragma("unroll") for (int m = 0; m < 4; ++m) _Pragma("unroll") for (int n = 0; n < 2; ++n) _Pragma("unroll") for (int k = 0; k < 2; ++k) \
;         acc[ai][bj][m][n] = __builtin_amdgcn_mfma_f32_16x16x32_bf16(Bt[n][k], At[m][k], acc[ai][bj][m][n], 0, 0, 0); __builtin_amdgcn_s_setprio(0); } while (0)
; #define PG8_WAIT_V(n) asm volatile("s_waitcnt vmcnt(" #n ")" ::: "memory")
; #define PG8_WAIT_L(n) asm volatile("s_waitcnt lgkmcnt(" #n ")" ::: "memory")
; #define PG8_BAR __builtin_amdgcn_s_barrier()
; #define PG8_SCHED __builtin_amdgcn_sched_barrier(0)
; template <class Epi, class Sched, bool ALIGN_EPI = false, bool SP2 = false>
; __device__ __forceinline__ void gemm_phase(PG8_LAS unsigned char* lds, const Gemm g, const Sched& S, const Epi& E) {
;     ...
;             PG8_LDA(At, 0, 1); PG8_STAGE(PG8_SB(0, 0), b2, voffB); PG8_STAGE(PG8_SB(0, 1), b2 + hstep, voffB);
;             PG8_WAIT_V(6); PG8_WAIT_L(0); PG8_BAR; PG8_MMA(1, 0, At, B0); PG8_MMA(1, 1, At, B1); PG8_BAR; PG8_SCHED;
	s_add_i32 s78, s79, s22
	v_lshl_add_u64 v[202:203], s[44:45], 0, v[204:205]
	s_mov_b32 m0, s78
	ds_read_b128 v[178:181], v145 offset:16384
	ds_read_b128 v[182:185], v145 offset:17408
	ds_read_b128 v[186:189], v145 offset:18432
	ds_read_b128 v[190:193], v145 offset:19456
	ds_read_b128 v[194:197], v145 offset:20480
	ds_read_b128 v[198:201], v145 offset:21504
	ds_read_b128 v[206:209], v145 offset:22528
	ds_read_b128 v[218:221], v145 offset:23552
	global_load_lds_dwordx4 v[202:203], off
	s_add_i32 m0, s78, 0x2000
	s_add_u32 s78, s44, 0x80000
	v_lshl_add_u64 v[222:223], s[44:45], 0, v[128:129]
	s_addc_u32 s79, s45, 0
	s_add_i32 s53, s53, s22
	global_load_lds_dwordx4 v[222:223], off
	v_lshl_add_u64 v[232:233], s[78:79], 0, v[204:205]
	s_mov_b32 m0, s53
	s_nop 0
	global_load_lds_dwordx4 v[232:233], off
	v_lshl_add_u64 v[232:233], s[78:79], 0, v[128:129]
	s_add_i32 m0, s53, 0x2000
	s_nop 0
	global_load_lds_dwordx4 v[232:233], off
	s_waitcnt vmcnt(6)
	s_waitcnt lgkmcnt(0)
	s_barrier
	v_mfma_f32_16x16x32_bf16 v[60:63], v[146:149], v[178:181], 0
	v_mfma_f32_16x16x32_bf16 v[56:59], v[154:157], v[178:181], 0
	v_mfma_f32_16x16x32_bf16 v[52:55], v[146:149], v[186:189], 0
	v_mfma_f32_16x16x32_bf16 v[44:47], v[154:157], v[186:189], 0
	v_mfma_f32_16x16x32_bf16 v[36:39], v[146:149], v[194:197], 0
	v_mfma_f32_16x16x32_bf16 v[28:31], v[154:157], v[194:197], 0
	v_mfma_f32_16x16x32_bf16 v[20:23], v[146:149], v[206:209], 0
	v_mfma_f32_16x16x32_bf16 v[12:15], v[154:157], v[206:209], 0
	v_mfma_f32_16x16x32_bf16 v[60:63], v[150:153], v[182:185], v[60:63]
	v_mfma_f32_16x16x32_bf16 v[56:59], v[158:161], v[182:185], v[56:59]
	v_mfma_f32_16x16x32_bf16 v[52:55], v[150:153], v[190:193], v[52:55]
	v_mfma_f32_16x16x32_bf16 v[44:47], v[158:161], v[190:193], v[44:47]
	v_mfma_f32_16x16x32_bf16 v[36:39], v[150:153], v[198:201], v[36:39]
	v_mfma_f32_16x16x32_bf16 v[28:31], v[158:161], v[198:201], v[28:31]
	v_mfma_f32_16x16x32_bf16 v[20:23], v[150:153], v[218:221], v[20:23]
	v_mfma_f32_16x16x32_bf16 v[12:15], v[158:161], v[218:221], v[12:15]
	v_mfma_f32_16x16x32_bf16 v[48:51], v[162:165], v[178:181], 0
	v_mfma_f32_16x16x32_bf16 v[40:43], v[170:173], v[178:181], 0
	v_mfma_f32_16x16x32_bf16 v[32:35], v[162:165], v[186:189], 0
	v_mfma_f32_16x16x32_bf16 v[24:27], v[170:173], v[186:189], 0
	v_mfma_f32_16x16x32_bf16 v[16:19], v[162:165], v[194:197], 0
	v_mfma_f32_16x16x32_bf16 v[8:11], v[170:173], v[194:197], 0
	v_mfma_f32_16x16x32_bf16 v[4:7], v[162:165], v[206:209], 0
	v_mfma_f32_16x16x32_bf16 v[0:3], v[170:173], v[206:209], 0
	v_mfma_f32_16x16x32_bf16 v[48:51], v[166:169], v[182:185], v[48:51]
	v_mfma_f32_16x16x32_bf16 v[40:43], v[174:177], v[182:185], v[40:43]
	v_mfma_f32_16x16x32_bf16 v[32:35], v[166:169], v[190:193], v[32:35]
	v_mfma_f32_16x16x32_bf16 v[24:27], v[174:177], v[190:193], v[24:27]
	v_mfma_f32_16x16x32_bf16 v[16:19], v[166:169], v[198:201], v[16:19]
	v_mfma_f32_16x16x32_bf16 v[8:11], v[174:177], v[198:201], v[8:11]
	v_mfma_f32_16x16x32_bf16 v[4:7], v[166:169], v[218:221], v[4:7]
	v_mfma_f32_16x16x32_bf16 v[0:3], v[174:177], v[218:221], v[0:3]
	s_barrier
	s_branch .Lpl_o

; __device__ __forceinline__ unsigned cvt_pk_bf16(float lo, float hi) { unsigned r; asm volatile("v_cvt_pk_bf16_f32 %0, %1, %2" : "=v"(r) : "v"(lo), "v"(hi)); return r; }
; #define PG8_STAGE(bufoff, gbase, voff) do { _Pragma("unroll") for (int _i = 0; _i < 2; ++_i) \
;         __builtin_amdgcn_global_load_lds((const unsigned*)((const char*)(gbase) + (voff)[_i]), (PG8_LAS unsigned*)(lds + (bufoff) + ldsw + _i * 8192), 16, 0, 0); } while (0)
; #define PG8_LDA(dst, b, h) do { _Pragma("unroll") for (int m = 0; m < 4; ++m) _Pragma("unroll") for (int k = 0; k < 2; ++k) dst[m][k] = *(const PG8_LAS bf16x8*)(lds + PG8_SA(b, h) + aoff + m * 2048 + k * 1024); } while (0)
; #define PG8_LDB(dst, b, h) do { _Pragma("unroll") for (int n = 0; n < 2; ++n) _Pragma("unroll") for (int k = 0; k < 2; ++k) dst[n][k] = *(const PG8_LAS bf16x8*)(lds + PG8_SB(b, h) + boff + n * 2048 + k * 1024); } while (0)
; #define PG8_SCHED __builtin_amdgcn_sched_barrier(0)
;     __device__ __forceinline__ void operator()(const f32x4 (&acc)[2][2][4][2], const Unit& u, int wr, int wc, int fr, int fq) const {
;     ...
;             for (int m = 0; m < 4; ++m) { bf16_t* rowp = O + (size_t)(row0 + ai * HALF + m * 16) * ldc + col0;
;                 float rsc = sc; if (rsmode == 1) { const float r_ = rs[row0 + ai * HALF + m * 16]; rsc = sc * (ACT == 2 ? r_ * r_ : r_); }
; #pragma unroll
;                 for (int bj = 0; bj < 2; ++bj) { f32x4 v0 = acc[ai][bj][m][0], v1 = acc[ai][bj][m][1];
;                     if (ACT == 2) {
; #pragma unroll
;                         for (int e = 0; e < 4; ++e) { const float a0 = fmaxf(v0[e], 0.f), a1 = fmaxf(v1[e], 0.f); v0[e] = a0 * a0; v1[e] = a1 * a1; } }
;                     v0 = v0 * cs[bj][0] * rsc; v1 = v1 * cs[bj][1] * rsc; u32x4 w; w.x = cvt_pk_bf16(v0[0], v0[1]); w.y = cvt_pk_bf16(v0[2], v0[3]); w.z = cvt_pk_bf16(v1[0], v1[1]); w.w = cvt_pk_bf16(v1[2], v1[3]);
;                     *(u32x4*)(rowp + bj * HALF) = w; } }
; template <class Epi, class Sched, bool ALIGN_EPI = false, bool SP2 = false>
; __device__ __forceinline__ void gemm_phase(PG8_LAS unsigned char* lds, const Gemm g, const Sched& S, const Epi& E) {
;     ...
;             PG8_LDB(B0, 0, 0); PG8_LDB(B1, 0, 1); PG8_SCHED; PG8_LDA(At, 0, 0); PG8_STAGE(PG8_SA(1, 0), a1, voffA); PG8_STAGE(PG8_SA(1, 1), a1 + hstep, voffA);
.LBB0_429:
	v_add_u32_e32 v174, 0x14000, v143
	ds_read_b128 v[162:165], v174
	ds_read_b128 v[166:169], v174 offset:1024
	ds_read_b128 v[170:173], v174 offset:2048
	ds_read_b128 v[174:177], v174 offset:3072
	ds_read_b128 v[178:181], v145
	ds_read_b128 v[182:185], v145 offset:1024
	ds_read_b128 v[186:189], v145 offset:2048
	ds_read_b128 v[190:193], v145 offset:3072
	ds_read_b128 v[194:197], v145 offset:4096
	ds_read_b128 v[198:201], v145 offset:5120
	ds_read_b128 v[206:209], v145 offset:6144
	ds_read_b128 v[218:221], v145 offset:7168
	v_lshl_add_u32 v140, s57, 8, v142
	v_lshl_or_b32 v138, s75, 8, v144
	v_ashrrev_i32_e32 v141, 31, v140
	v_ashrrev_i32_e32 v139, 31, v138
	v_lshlrev_b64 v[146:147], 12, v[140:141]
	v_lshl_add_u64 v[146:147], s[8:9], 0, v[146:147]
	v_lshlrev_b64 v[148:149], 1, v[138:139]
	v_lshl_add_u64 v[138:139], v[146:147], 0, v[148:149]
	v_cvt_pk_bf16_f32 v124, v124, v125
	v_cvt_pk_bf16_f32 v125, v126, v127
	v_cvt_pk_bf16_f32 v126, v120, v121
	v_cvt_pk_bf16_f32 v127, v122, v123
	global_store_dwordx4 v[138:139], v[124:127], off
	v_cvt_pk_bf16_f32 v112, v112, v113
	v_cvt_pk_bf16_f32 v113, v114, v115
	v_cvt_pk_bf16_f32 v114, v104, v105
	v_or_b32_e32 v104, 16, v140
	v_ashrrev_i32_e32 v105, 31, v104
	v_lshlrev_b64 v[104:105], 12, v[104:105]
	v_lshl_add_u64 v[104:105], s[8:9], 0, v[104:105]
	v_cvt_pk_bf16_f32 v115, v106, v107
	global_store_dwordx4 v[138:139], v[112:115], off offset:256
	s_mov_b64 s[16:17], 0x90000
	s_mov_b64 s[0:1], 0xa0000
	v_lshl_add_u64 v[112:113], v[104:105], 0, v[148:149]
	v_cvt_pk_bf16_f32 v104, v116, v117
	v_cvt_pk_bf16_f32 v105, v118, v119
	v_cvt_pk_bf16_f32 v106, v108, v109
	v_cvt_pk_bf16_f32 v107, v110, v111
	global_store_dwordx4 v[112:113], v[104:107], off
	v_cvt_pk_bf16_f32 v96, v96, v97
	v_cvt_pk_bf16_f32 v97, v98, v99
	v_cvt_pk_bf16_f32 v98, v88, v89
	v_or_b32_e32 v88, 32, v140
	v_ashrrev_i32_e32 v89, 31, v88
	v_lshlrev_b64 v[88:89], 12, v[88:89]
	v_lshl_add_u64 v[88:89], s[8:9], 0, v[88:89]
	v_cvt_pk_bf16_f32 v99, v90, v91
	global_store_dwordx4 v[112:113], v[96:99], off offset:256
	s_nop 1
	v_lshl_add_u64 v[96:97], v[88:89], 0, v[148:149]
	v_cvt_pk_bf16_f32 v88, v100, v101
	v_cvt_pk_bf16_f32 v89, v102, v103
	v_cvt_pk_bf16_f32 v90, v92, v93
	v_cvt_pk_bf16_f32 v91, v94, v95
	global_store_dwordx4 v[96:97], v[88:91], off
	v_cvt_pk_bf16_f32 v80, v80, v81
	v_cvt_pk_bf16_f32 v81, v82, v83
	v_cvt_pk_bf16_f32 v82, v72, v73
	v_or_b32_e32 v72, 48, v140
	v_ashrrev_i32_e32 v73, 31, v72
	v_lshlrev_b64 v[72:73], 12, v[72:73]
	v_lshl_add_u64 v[72:73], s[8:9], 0, v[72:73]
	v_cvt_pk_bf16_f32 v83, v74, v75
	global_store_dwordx4 v[96:97], v[80:83], off offset:256
	s_nop 1
	v_lshl_add_u64 v[80:81], v[72:73], 0, v[148:149]
	v_cvt_pk_bf16_f32 v72, v84, v85
	v_cvt_pk_bf16_f32 v73, v86, v87
	v_cvt_pk_bf16_f32 v74, v76, v77
	v_cvt_pk_bf16_f32 v75, v78, v79
	global_store_dwordx4 v[80:81], v[72:75], off
	v_cvt_pk_bf16_f32 v68, v68, v69
	v_cvt_pk_bf16_f32 v69, v70, v71
	v_cvt_pk_bf16_f32 v70, v64, v65
	v_cvt_pk_bf16_f32 v71, v66, v67
	global_store_dwordx4 v[80:81], v[68:71], off offset:256
	v_cvt_pk_bf16_f32 v60, v60, v61
	v_cvt_pk_bf16_f32 v61, v62, v63
	v_cvt_pk_bf16_f32 v62, v56, v57
	v_add_co_u32_e32 v56, vcc, s85, v138
	v_lshl_add_u64 v[64:65], v[138:139], 0, s[24:25]
	s_nop 0
	v_addc_co_u32_e32 v57, vcc, 0, v139, vcc
	v_cvt_pk_bf16_f32 v63, v58, v59
	global_store_dwordx4 v[56:57], v[60:63], off
	v_cvt_pk_bf16_f32 v48, v48, v49
	v_cvt_pk_bf16_f32 v49, v50, v51
	v_cvt_pk_bf16_f32 v50, v40, v41
	v_cvt_pk_bf16_f32 v51, v42, v43
	global_store_dwordx4 v[64:65], v[48:51], off offset:256
	v_cvt_pk_bf16_f32 v40, v52, v53
	v_cvt_pk_bf16_f32 v41, v54, v55
	v_cvt_pk_bf16_f32 v42, v44, v45
	v_cvt_pk_bf16_f32 v43, v46, v47
	s_nop 1
	v_lshl_add_u64 v[48:49], v[138:139], 0, s[16:17]
	s_mov_b32 s16, 0x90000
	v_add_co_u32_e32 v44, vcc, s16, v138
	s_mov_b32 s16, 0xa0000
	s_nop 0
	v_addc_co_u32_e32 v45, vcc, 0, v139, vcc
	global_store_dwordx4 v[44:45], v[40:43], off
	v_cvt_pk_bf16_f32 v32, v32, v33
	v_cvt_pk_bf16_f32 v33, v34, v35
	v_cvt_pk_bf16_f32 v34, v24, v25
	v_cvt_pk_bf16_f32 v35, v26, v27
	global_store_dwordx4 v[48:49], v[32:35], off offset:256
	v_cvt_pk_bf16_f32 v24, v36, v37
	v_cvt_pk_bf16_f32 v25, v38, v39
	v_cvt_pk_bf16_f32 v26, v28, v29
	v_add_co_u32_e32 v28, vcc, s16, v138
	s_nop 0
	v_lshl_add_u64 v[32:33], v[138:139], 0, s[0:1]
	v_addc_co_u32_e32 v29, vcc, 0, v139, vcc
	v_cvt_pk_bf16_f32 v27, v30, v31
	global_store_dwordx4 v[28:29], v[24:27], off
	v_cvt_pk_bf16_f32 v16, v16, v17
	v_cvt_pk_bf16_f32 v17, v18, v19
	v_cvt_pk_bf16_f32 v18, v8, v9
	v_cvt_pk_bf16_f32 v19, v10, v11
	global_store_dwordx4 v[32:33], v[16:19], off offset:256
	v_cvt_pk_bf16_f32 v8, v20, v21
	v_cvt_pk_bf16_f32 v9, v22, v23
	v_cvt_pk_bf16_f32 v10, v12, v13
	v_add_co_u32_e32 v12, vcc, s81, v138
	s_nop 0
	v_lshl_add_u64 v[16:17], v[138:139], 0, s[54:55]
	v_addc_co_u32_e32 v13, vcc, 0, v139, vcc
	s_andn2_b64 vcc, exec, s[38:39]
	s_mov_b64 s[16:17], -1
	v_cvt_pk_bf16_f32 v11, v14, v15
	global_store_dwordx4 v[12:13], v[8:11], off
	v_cvt_pk_bf16_f32 v4, v4, v5
	v_cvt_pk_bf16_f32 v5, v6, v7
	v_cvt_pk_bf16_f32 v6, v0, v1
	v_cvt_pk_bf16_f32 v7, v2, v3
	global_store_dwordx4 v[16:17], v[4:7], off offset:256
	s_cbranch_vccnz .LBB0_418
	s_andn2_b64 vcc, exec, s[6:7]
	s_cbranch_vccnz .LBB0_417
	s_barrier
	s_branch .LBB0_417

; #define PG8_STAGE(bufoff, gbase, voff) do { _Pragma("unroll") for (int _i = 0; _i < 2; ++_i) \
;         __builtin_amdgcn_global_load_lds((const unsigned*)((const char*)(gbase) + (voff)[_i]), (PG8_LAS unsigned*)(lds + (bufoff) + ldsw + _i * 8192), 16, 0, 0); } while (0)
; #define PG8_LDA(dst, b, h) do { _Pragma("unroll") for (int m = 0; m < 4; ++m) _Pragma("unroll") for (int k = 0; k < 2; ++k) dst[m][k] = *(const PG8_LAS bf16x8*)(lds + PG8_SA(b, h) + aoff + m * 2048 + k * 1024); } while (0)
; #define PG8_LDB(dst, b, h) do { _Pragma("unroll") for (int n = 0; n < 2; ++n) _Pragma("unroll") for (int k = 0; k < 2; ++k) dst[n][k] = *(const PG8_LAS bf16x8*)(lds + PG8_SB(b, h) + boff + n * 2048 + k * 1024); } while (0)
; #define PG8_WAIT_V(n) asm volatile("s_waitcnt vmcnt(" #n ")" ::: "memory")
; #define PG8_BAR __builtin_amdgcn_s_barrier()
; #define PG8_SCHED __builtin_amdgcn_sched_barrier(0)
; template <class Epi, class Sched, bool ALIGN_EPI = false, bool SP2 = false>
; __device__ __forceinline__ void gemm_phase(PG8_LAS unsigned char* lds, const Gemm g, const Sched& S, const Epi& E) {
;     ...
;     const unsigned ldsw = (unsigned)wid * 1024u;
;     const int aoff = lds_byte(wr * 64 + fr, fq * 8), boff = lds_byte(wc * 32 + fr, fq * 8);
;     ...
;     Unit cur, nxt; int ui = 0;
;     if (!S.next(0, cur)) return;
;     f32x4 acc[2][2][4][2];
; #pragma unroll
;     for (int a = 0; a < 2; ++a)
; #pragma unroll
;         for (int b = 0; b < 2; ++b)
; #pragma unroll
;             for (int m = 0; m < 4; ++m)
; #pragma unroll
;                 for (int n = 0; n < 2; ++n) acc[a][b][m][n] = (f32x4){0.f, 0.f, 0.f, 0.f};
;     bf16x8 At[4][2], B0[2][2], B1[2][2];
;     const char* cA = (const char*)g.A + (size_t)cur.pm * tstep; const char* cB = (const char*)g.Bt + (size_t)cur.pn * tstep;
;     S.a_ready(cur);
;     if constexpr (SP2) {
;         PG8_STAGE(PG8_SB(0, 0), cB, voffB); PG8_STAGE(PG8_SB(0, 1), cB + hstep, voffB); PG8_STAGE(PG8_SA(0, 0), cA, voffA); PG8_STAGE(PG8_SA(0, 1), cA + hstep, voffA);
;         if (wr == 1) PG8_BAR;
;         PG8_WAIT_V(2); PG8_BAR;
;         PG8_STAGE(PG8_SB(1, 0), cB + kstep, voffB); PG8_STAGE(PG8_SB(1, 1), cB + hstep + kstep, voffB);
;         PG8_WAIT_V(4); PG8_BAR;
;     ...
;             PG8_LDB(B0, 0, 0); PG8_LDB(B1, 0, 1); PG8_SCHED; PG8_LDA(At, 0, 0); PG8_STAGE(PG8_SA(1, 0), a1, voffA); PG8_STAGE(PG8_SA(1, 1), a1 + hstep, voffA);
.LBB0_692:
	s_add_u32 s8, s8, 0x35000000
	v_lshrrev_b32_e32 v12, 1, v10
	s_addc_u32 s9, s9, 0
	v_and_b32_e32 v11, 15, v10
	v_and_b32_e32 v12, 24, v12
	s_lshl_b32 s11, s11, 5
	v_lshl_or_b32 v142, s40, 6, v11
	v_lshlrev_b32_e32 v13, 1, v12
	s_lshl_b32 s38, s40, 13
	v_lshlrev_b32_e32 v10, 2, v10
	s_and_b32 s40, s11, 0x60
	s_add_i32 m0, s36, 0x18000
	v_lshl_add_u64 v[0:1], v[0:1], 0, s[26:27]
	v_lshl_or_b32 v11, v11, 6, v13
	v_and_b32_e32 v10, 32, v10
	s_lshl_b32 s11, s40, 7
	s_waitcnt vmcnt(2)
	s_barrier
	global_load_lds_dwordx4 v[0:1], off
	s_add_i32 m0, s36, 0x1a000
	v_bitop3_b32 v13, v11, s38, v10 bitop3:0xde
	s_add_u32 s38, s44, 0x200080
	v_lshl_add_u64 v[0:1], v[2:3], 0, s[26:27]
	s_addc_u32 s39, s45, 0
	global_load_lds_dwordx4 v[0:1], off
	s_add_i32 m0, s36, 0x1c000
	v_lshl_add_u64 v[0:1], s[38:39], 0, v[204:205]
	global_load_lds_dwordx4 v[0:1], off
	v_lshl_add_u64 v[0:1], s[38:39], 0, v[128:129]
	s_add_i32 m0, s36, 0x1e000
	s_cmpk_lt_u32 s10, 0x100
	global_load_lds_dwordx4 v[0:1], off
	v_lshlrev_b32_e32 v0, 17, v8
	v_and_b32_e32 v0, 0xfffc0000, v0
	v_lshl_add_u32 v0, v7, 14, v0
	v_and_b32_e32 v1, 1, v8
	v_lshl_or_b32 v0, v1, 6, v0
	v_lshl_add_u32 v134, v9, 1, v0
	v_lshlrev_b32_e32 v0, 17, v4
	v_and_b32_e32 v0, 0xfffc0000, v0
	s_waitcnt vmcnt(4)
	v_lshl_add_u32 v0, v5, 14, v0
	v_and_b32_e32 v1, 1, v4
	v_lshl_or_b32 v0, v1, 6, v0
	v_readlane_b32 s38, v255, 20
	v_mov_b32_e32 v133, v205
	v_mov_b32_e32 v131, v205
	v_bitop3_b32 v143, v11, s11, v10 bitop3:0xde
	s_cselect_b64 s[10:11], -1, 0
	v_or_b32_e32 v144, s40, v12
	v_mov_b32_e32 v135, v205
	v_lshl_add_u32 v136, v6, 1, v0
	v_mov_b32_e32 v137, v205
	s_mov_b32 s84, 0
	v_add_u32_e32 v145, 0, v13
	v_readlane_b32 s95, v254, 60
	s_nop 3
	s_bfe_u32 s32, s38, 0x10002
	s_lshl_b32 s95, s95, 1
	s_add_i32 s95, s95, s32
	s_bitset0_b32 s38, 2
	s_mov_b32 s94, s38
	s_barrier
	v_readlane_b32 s39, v255, 21
	v_add_u32_e32 v174, 0x14000, v143
	ds_read_b128 v[162:165], v174
	ds_read_b128 v[166:169], v174 offset:1024
	ds_read_b128 v[170:173], v174 offset:2048
	ds_read_b128 v[174:177], v174 offset:3072
	ds_read_b128 v[178:181], v145
	ds_read_b128 v[182:185], v145 offset:1024
	ds_read_b128 v[186:189], v145 offset:2048
	ds_read_b128 v[190:193], v145 offset:3072
	ds_read_b128 v[194:197], v145 offset:4096
	ds_read_b128 v[198:201], v145 offset:5120
	ds_read_b128 v[206:209], v145 offset:6144
	ds_read_b128 v[218:221], v145 offset:7168
	s_branch .LBB0_695

; #define PG8_STAGE(bufoff, gbase, voff) do { _Pragma("unroll") for (int _i = 0; _i < 2; ++_i) \
;         __builtin_amdgcn_global_load_lds((const unsigned*)((const char*)(gbase) + (voff)[_i]), (PG8_LAS unsigned*)(lds + (bufoff) + ldsw + _i * 8192), 16, 0, 0); } while (0)
; #define PG8_LDA(dst, b, h) do { _Pragma("unroll") for (int m = 0; m < 4; ++m) _Pragma("unroll") for (int k = 0; k < 2; ++k) dst[m][k] = *(const PG8_LAS bf16x8*)(lds + PG8_SA(b, h) + aoff + m * 2048 + k * 1024); } while (0)
; #define PG8_LDB(dst, b, h) do { _Pragma("unroll") for (int n = 0; n < 2; ++n) _Pragma("unroll") for (int k = 0; k < 2; ++k) dst[n][k] = *(const PG8_LAS bf16x8*)(lds + PG8_SB(b, h) + boff + n * 2048 + k * 1024); } while (0)
; #define PG8_MMA(ai, bj, At, Bt) do { __builtin_amdgcn_s_setprio(1); _Pragma("unroll") for (int m = 0; m < 4; ++m) _Pragma("unroll") for (int n = 0; n < 2; ++n) _Pragma("unroll") for (int k = 0; k < 2; ++k) \
;         acc[ai][bj][m][n] = __builtin_amdgcn_mfma_f32_16x16x32_bf16(Bt[n][k], At[m][k], acc[ai][bj][m][n], 0, 0, 0); __builtin_amdgcn_s_setprio(0); } while (0)
; #define PG8_WAIT_V(n) asm volatile("s_waitcnt vmcnt(" #n ")" ::: "memory")
; #define PG8_WAIT_L(n) asm volatile("s_waitcnt lgkmcnt(" #n ")" ::: "memory")
; template <class Epi, class Sched, bool ALIGN_EPI = false, bool SP2 = false>
; __device__ __forceinline__ void gemm_phase(PG8_LAS unsigned char* lds, const Gemm g, const Sched& S, const Epi& E) {
;     ...
;         const bool has_next = S.next(ui + 1, nxt);
;         const char* nA = has_next ? (const char*)g.A + (size_t)nxt.pm * tstep : cA; const char* nB = has_next ? (const char*)g.Bt + (size_t)nxt.pn * tstep : cB;
;         for (int t = 0; t < nt; t += 2) {
;             const bool last = (t == nt - 2);
;             const char* a1 = cA + (size_t)(t + 1) * kstep;
;             const char* a2 = last ? nA : cA + (size_t)(t + 2) * kstep; const char* b2 = last ? nB : cB + (size_t)(t + 2) * kstep;
;             const char* a3 = a2 + kstep; const char* b3 = b2 + kstep;
;             if (last && has_next) S.a_ready(nxt);
;             if constexpr (SP2) {
;             PG8_LDB(B0, 0, 0); PG8_LDB(B1, 0, 1); PG8_SCHED; PG8_LDA(At, 0, 0); PG8_STAGE(PG8_SA(1, 0), a1, voffA); PG8_STAGE(PG8_SA(1, 1), a1 + hstep, voffA);
;             PG8_WAIT_V(8); PG8_WAIT_L(0); PG8_BAR; PG8_MMA(0, 0, At, B0); PG8_MMA(0, 1, At, B1); PG8_BAR; PG8_SCHED;
.LBB0_701:
	s_ashr_i32 s47, s46, 31
	s_lshl_b64 s[38:39], s[46:47], 22
	s_add_u32 s72, s20, s38
	s_addc_u32 s73, s21, s39
	s_and_b64 s[38:39], s[40:41], exec
	s_cselect_b32 s47, s73, s17
	s_cselect_b32 s70, s72, s16
	s_ashr_i32 s43, s42, 31
	s_lshl_b64 s[38:39], s[42:43], 22
	s_add_u32 s76, s23, s38
	s_addc_u32 s77, s34, s39
	s_and_b64 s[38:39], s[40:41], exec
	s_cselect_b32 s43, s77, s45
	s_cselect_b32 s71, s76, s44
	s_add_u32 s97, s44, 0x100
	s_addc_u32 vcc_lo, s45, 0
	v_lshl_add_u64 v[138:139], s[16:17], 0, v[134:135]
	v_lshl_add_u64 v[140:141], s[16:17], 0, v[136:137]
	s_mov_b32 s52, -2
	s_mov_b64 s[88:89], 0
	s_add_u32 s38, s16, s88
	s_addc_u32 s39, s17, s89
	s_add_u32 s38, s38, 0x100
	s_addc_u32 s39, s39, 0
	s_add_u32 s44, s97, s88
	s_addc_u32 s45, vcc_lo, s89
	s_add_i32 s53, 0, 0x10000
	s_cmpk_eq_i32 s88, 0x3f00
	s_cselect_b32 s45, s43, s45
	s_cselect_b32 s44, s71, s44
	s_cselect_b32 s69, s47, s39
	s_cselect_b32 s68, s70, s38
	s_add_i32 s78, 0, 0x14000
	v_add_u32_e32 v158, s53, v143
	ds_read_b128 v[146:149], v158
	ds_read_b128 v[150:153], v158 offset:1024
	ds_read_b128 v[154:157], v158 offset:2048
	ds_read_b128 v[158:161], v158 offset:3072
	v_lshl_add_u64 v[202:203], v[138:139], 0, s[88:89]
	v_lshl_add_u64 v[222:223], v[202:203], 0, s[26:27]
	s_add_i32 m0, s36, 0x8000
	global_load_lds_dwordx4 v[222:223], off
	v_lshl_add_u64 v[222:223], v[140:141], 0, s[88:89]
	v_lshl_add_u64 v[232:233], v[222:223], 0, s[26:27]
	s_add_i32 m0, s36, 0xa000
	v_lshl_add_u64 v[202:203], v[202:203], 0, s[90:91]
	global_load_lds_dwordx4 v[232:233], off
	s_add_i32 m0, s36, 0xc000
	s_nop 0
	global_load_lds_dwordx4 v[202:203], off
	v_lshl_add_u64 v[202:203], v[222:223], 0, s[90:91]
	s_add_i32 m0, s36, 0xe000
	s_nop 0
	global_load_lds_dwordx4 v[202:203], off
	s_waitcnt vmcnt(8)
	s_waitcnt lgkmcnt(0)
	s_barrier
	v_mfma_f32_16x16x32_bf16 v[124:127], v[146:149], v[178:181], 0
	v_mfma_f32_16x16x32_bf16 v[120:123], v[154:157], v[178:181], 0
	v_mfma_f32_16x16x32_bf16 v[116:119], v[146:149], v[186:189], 0
	v_mfma_f32_16x16x32_bf16 v[108:111], v[154:157], v[186:189], 0
	v_mfma_f32_16x16x32_bf16 v[100:103], v[146:149], v[194:197], 0
	v_mfma_f32_16x16x32_bf16 v[92:95], v[154:157], v[194:197], 0
	v_mfma_f32_16x16x32_bf16 v[84:87], v[146:149], v[206:209], 0
	v_mfma_f32_16x16x32_bf16 v[76:79], v[154:157], v[206:209], 0
	v_mfma_f32_16x16x32_bf16 v[124:127], v[150:153], v[182:185], v[124:127]
	v_mfma_f32_16x16x32_bf16 v[120:123], v[158:161], v[182:185], v[120:123]
	v_mfma_f32_16x16x32_bf16 v[116:119], v[150:153], v[190:193], v[116:119]
	v_mfma_f32_16x16x32_bf16 v[108:111], v[158:161], v[190:193], v[108:111]
	v_mfma_f32_16x16x32_bf16 v[100:103], v[150:153], v[198:201], v[100:103]
	v_mfma_f32_16x16x32_bf16 v[92:95], v[158:161], v[198:201], v[92:95]
	v_mfma_f32_16x16x32_bf16 v[84:87], v[150:153], v[218:221], v[84:87]
	v_mfma_f32_16x16x32_bf16 v[76:79], v[158:161], v[218:221], v[76:79]
	v_mfma_f32_16x16x32_bf16 v[112:115], v[162:165], v[178:181], 0
	v_mfma_f32_16x16x32_bf16 v[104:107], v[170:173], v[178:181], 0
	v_mfma_f32_16x16x32_bf16 v[96:99], v[162:165], v[186:189], 0
	v_mfma_f32_16x16x32_bf16 v[88:91], v[170:173], v[186:189], 0
	v_mfma_f32_16x16x32_bf16 v[80:83], v[162:165], v[194:197], 0
	v_mfma_f32_16x16x32_bf16 v[72:75], v[170:173], v[194:197], 0
	v_mfma_f32_16x16x32_bf16 v[68:71], v[162:165], v[206:209], 0
	v_mfma_f32_16x16x32_bf16 v[64:67], v[170:173], v[206:209], 0
	v_mfma_f32_16x16x32_bf16 v[112:115], v[166:169], v[182:185], v[112:115]
	v_mfma_f32_16x16x32_bf16 v[104:107], v[174:177], v[182:185], v[104:107]
	v_mfma_f32_16x16x32_bf16 v[96:99], v[166:169], v[190:193], v[96:99]
	v_mfma_f32_16x16x32_bf16 v[88:91], v[174:177], v[190:193], v[88:91]
	v_mfma_f32_16x16x32_bf16 v[80:83], v[166:169], v[198:201], v[80:83]
	v_mfma_f32_16x16x32_bf16 v[72:75], v[174:177], v[198:201], v[72:75]
	v_mfma_f32_16x16x32_bf16 v[68:71], v[166:169], v[218:221], v[68:71]
	v_mfma_f32_16x16x32_bf16 v[64:67], v[174:177], v[218:221], v[64:67]
	s_barrier
; #define PG8_STAGE(bufoff, gbase, voff) do { _Pragma("unroll") for (int _i = 0; _i < 2; ++_i) \
;         __builtin_amdgcn_global_load_lds((const unsigned*)((const char*)(gbase) + (voff)[_i]), (PG8_LAS unsigned*)(lds + (bufoff) + ldsw + _i * 8192), 16, 0, 0); } while (0)
; #define PG8_LDA(dst, b, h) do { _Pragma("unroll") for (int m = 0; m < 4; ++m) _Pragma("unroll") for (int k = 0; k < 2; ++k) dst[m][k] = *(const PG8_LAS bf16x8*)(lds + PG8_SA(b, h) + aoff + m * 2048 + k * 1024); } while (0)
; #define PG8_MMA(ai, bj, At, Bt) do { __builtin_amdgcn_s_setprio(1); _Pragma("unroll") for (int m = 0; m < 4; ++m) _Pragma("unroll") for (int n = 0; n < 2; ++n) _Pragma("unroll") for (int k = 0; k < 2; ++k) \
;         acc[ai][bj][m][n] = __builtin_amdgcn_mfma_f32_16x16x32_bf16(Bt[n][k], At[m][k], acc[ai][bj][m][n], 0, 0, 0); __builtin_amdgcn_s_setprio(0); } while (0)
; #define PG8_WAIT_V(n) asm volatile("s_waitcnt vmcnt(" #n ")" ::: "memory")
; #define PG8_WAIT_L(n) asm volatile("s_waitcnt lgkmcnt(" #n ")" ::: "memory")
; #define PG8_BAR __builtin_amdgcn_s_barrier()
; #define PG8_SCHED __builtin_amdgcn_sched_barrier(0)
; template <class Epi, class Sched, bool ALIGN_EPI = false, bool SP2 = false>
; __device__ __forceinline__ void gemm_phase(PG8_LAS unsigned char* lds, const Gemm g, const Sched& S, const Epi& E) {
;     ...
;             PG8_LDA(At, 0, 1); PG8_STAGE(PG8_SB(0, 0), b2, voffB); PG8_STAGE(PG8_SB(0, 1), b2 + hstep, voffB);
;             PG8_WAIT_V(6); PG8_WAIT_L(0); PG8_BAR; PG8_MMA(1, 0, At, B0); PG8_MMA(1, 1, At, B1); PG8_BAR; PG8_SCHED;
	s_add_i32 s38, s53, s35
	v_lshl_add_u64 v[202:203], s[44:45], 0, v[204:205]
	s_mov_b32 m0, s38
	ds_read_b128 v[178:181], v145 offset:16384
	ds_read_b128 v[182:185], v145 offset:17408
	ds_read_b128 v[186:189], v145 offset:18432
	ds_read_b128 v[190:193], v145 offset:19456
	ds_read_b128 v[194:197], v145 offset:20480
	ds_read_b128 v[198:201], v145 offset:21504
	ds_read_b128 v[206:209], v145 offset:22528
	ds_read_b128 v[218:221], v145 offset:23552
	global_load_lds_dwordx4 v[202:203], off
	s_add_i32 m0, s38, 0x2000
	s_add_u32 s38, s44, 0x200000
	v_lshl_add_u64 v[222:223], s[44:45], 0, v[128:129]
	s_addc_u32 s39, s45, 0
	s_add_i32 s53, s78, s35
	global_load_lds_dwordx4 v[222:223], off
	v_lshl_add_u64 v[232:233], s[38:39], 0, v[204:205]
	s_mov_b32 m0, s53
	s_nop 0
	global_load_lds_dwordx4 v[232:233], off
	v_lshl_add_u64 v[232:233], s[38:39], 0, v[128:129]
	s_add_i32 m0, s53, 0x2000
	s_nop 0
	global_load_lds_dwordx4 v[232:233], off
	s_waitcnt vmcnt(6)
	s_waitcnt lgkmcnt(0)
	s_barrier
	v_mfma_f32_16x16x32_bf16 v[60:63], v[146:149], v[178:181], 0
	v_mfma_f32_16x16x32_bf16 v[56:59], v[154:157], v[178:181], 0
	v_mfma_f32_16x16x32_bf16 v[52:55], v[146:149], v[186:189], 0
	v_mfma_f32_16x16x32_bf16 v[44:47], v[154:157], v[186:189], 0
	v_mfma_f32_16x16x32_bf16 v[36:39], v[146:149], v[194:197], 0
	v_mfma_f32_16x16x32_bf16 v[28:31], v[154:157], v[194:197], 0
	v_mfma_f32_16x16x32_bf16 v[20:23], v[146:149], v[206:209], 0
	v_mfma_f32_16x16x32_bf16 v[12:15], v[154:157], v[206:209], 0
	v_mfma_f32_16x16x32_bf16 v[60:63], v[150:153], v[182:185], v[60:63]
	v_mfma_f32_16x16x32_bf16 v[56:59], v[158:161], v[182:185], v[56:59]
	v_mfma_f32_16x16x32_bf16 v[52:55], v[150:153], v[190:193], v[52:55]
	v_mfma_f32_16x16x32_bf16 v[44:47], v[158:161], v[190:193], v[44:47]
	v_mfma_f32_16x16x32_bf16 v[36:39], v[150:153], v[198:201], v[36:39]
	v_mfma_f32_16x16x32_bf16 v[28:31], v[158:161], v[198:201], v[28:31]
	v_mfma_f32_16x16x32_bf16 v[20:23], v[150:153], v[218:221], v[20:23]
	v_mfma_f32_16x16x32_bf16 v[12:15], v[158:161], v[218:221], v[12:15]
	v_mfma_f32_16x16x32_bf16 v[48:51], v[162:165], v[178:181], 0
	v_mfma_f32_16x16x32_bf16 v[40:43], v[170:173], v[178:181], 0
	v_mfma_f32_16x16x32_bf16 v[32:35], v[162:165], v[186:189], 0
	v_mfma_f32_16x16x32_bf16 v[24:27], v[170:173], v[186:189], 0
	v_mfma_f32_16x16x32_bf16 v[16:19], v[162:165], v[194:197], 0
	v_mfma_f32_16x16x32_bf16 v[8:11], v[170:173], v[194:197], 0
	v_mfma_f32_16x16x32_bf16 v[4:7], v[162:165], v[206:209], 0
	v_mfma_f32_16x16x32_bf16 v[0:3], v[170:173], v[206:209], 0
	v_mfma_f32_16x16x32_bf16 v[48:51], v[166:169], v[182:185], v[48:51]
	v_mfma_f32_16x16x32_bf16 v[40:43], v[174:177], v[182:185], v[40:43]
	v_mfma_f32_16x16x32_bf16 v[32:35], v[166:169], v[190:193], v[32:35]
	v_mfma_f32_16x16x32_bf16 v[24:27], v[174:177], v[190:193], v[24:27]
	v_mfma_f32_16x16x32_bf16 v[16:19], v[166:169], v[198:201], v[16:19]
	v_mfma_f32_16x16x32_bf16 v[8:11], v[174:177], v[198:201], v[8:11]
	v_mfma_f32_16x16x32_bf16 v[4:7], v[166:169], v[218:221], v[4:7]
	v_mfma_f32_16x16x32_bf16 v[0:3], v[174:177], v[218:221], v[0:3]
	s_barrier
	s_branch .Lpl_down

; __device__ __forceinline__ unsigned cvt_pk_bf16(float lo, float hi) { unsigned r; asm volatile("v_cvt_pk_bf16_f32 %0, %1, %2" : "=v"(r) : "v"(lo), "v"(hi)); return r; }
; #define PG8_STAGE(bufoff, gbase, voff) do { _Pragma("unroll") for (int _i = 0; _i < 2; ++_i) \
;         __builtin_amdgcn_global_load_lds((const unsigned*)((const char*)(gbase) + (voff)[_i]), (PG8_LAS unsigned*)(lds + (bufoff) + ldsw + _i * 8192), 16, 0, 0); } while (0)
;     __device__ __forceinline__ void operator()(const f32x4 (&acc)[2][2][4][2], const Unit& u, int wr, int wc, int fr, int fq) const {
;         const int row0 = u.pm * BM + wr * 64 + fr; const int colt = u.pn * BM;
;         const float sc = (colt < scale_cols) ? scale0 : 1.f;
;         const int col0 = colt + wc * 32 + 8 * fq;
;         f32x4 cs[2][2];
; #pragma unroll
;         for (int bj = 0; bj < 2; ++bj) { cs[bj][0] = (f32x4){1.f, 1.f, 1.f, 1.f}; cs[bj][1] = cs[bj][0]; if (rsmode == 2) { cs[bj][0] = *(const f32x4*)(rs + col0 + bj * HALF); cs[bj][1] = *(const f32x4*)(rs + col0 + bj * HALF + 4); } }
; #pragma unroll
;         for (int ai = 0; ai < 2; ++ai)
; #pragma unroll
;             for (int m = 0; m < 4; ++m) { bf16_t* rowp = O + (size_t)(row0 + ai * HALF + m * 16) * ldc + col0;
;                 float rsc = sc; if (rsmode == 1) { const float r_ = rs[row0 + ai * HALF + m * 16]; rsc = sc * (ACT == 2 ? r_ * r_ : r_); }
; #pragma unroll
;                 for (int bj = 0; bj < 2; ++bj) { f32x4 v0 = acc[ai][bj][m][0], v1 = acc[ai][bj][m][1];
;                     if (ACT == 2) {
; #pragma unroll
;                         for (int e = 0; e < 4; ++e) { const float a0 = fmaxf(v0[e], 0.f), a1 = fmaxf(v1[e], 0.f); v0[e] = a0 * a0; v1[e] = a1 * a1; } }
;                     v0 = v0 * cs[bj][0] * rsc; v1 = v1 * cs[bj][1] * rsc; u32x4 w; w.x = cvt_pk_bf16(v0[0], v0[1]); w.y = cvt_pk_bf16(v0[2], v0[3]); w.z = cvt_pk_bf16(v1[0], v1[1]); w.w = cvt_pk_bf16(v1[2], v1[3]);
;                     *(u32x4*)(rowp + bj * HALF) = w; } }
; template <class Epi, class Sched, bool ALIGN_EPI = false, bool SP2 = false>
; __device__ __forceinline__ void gemm_phase(PG8_LAS unsigned char* lds, const Gemm g, const Sched& S, const Epi& E) {
;     ...
;             PG8_LDB(B0, 0, 0); PG8_LDB(B1, 0, 1); PG8_SCHED; PG8_LDA(At, 0, 0); PG8_STAGE(PG8_SA(1, 0), a1, voffA); PG8_STAGE(PG8_SA(1, 1), a1 + hstep, voffA);
.LBB0_705:
	v_add_u32_e32 v174, 0x14000, v143
	ds_read_b128 v[162:165], v174
	ds_read_b128 v[166:169], v174 offset:1024
	ds_read_b128 v[170:173], v174 offset:2048
	ds_read_b128 v[174:177], v174 offset:3072
	ds_read_b128 v[178:181], v145
	ds_read_b128 v[182:185], v145 offset:1024
	ds_read_b128 v[186:189], v145 offset:2048
	ds_read_b128 v[190:193], v145 offset:3072
	ds_read_b128 v[194:197], v145 offset:4096
	ds_read_b128 v[198:201], v145 offset:5120
	ds_read_b128 v[206:209], v145 offset:6144
	ds_read_b128 v[218:221], v145 offset:7168
	v_lshl_add_u32 v140, s94, 8, v142
	v_lshl_or_b32 v138, s95, 8, v144
	v_ashrrev_i32_e32 v141, 31, v140
	v_ashrrev_i32_e32 v139, 31, v138
	v_lshlrev_b64 v[146:147], 12, v[140:141]
	v_lshl_add_u64 v[146:147], s[8:9], 0, v[146:147]
	v_lshlrev_b64 v[148:149], 1, v[138:139]
	v_lshl_add_u64 v[138:139], v[146:147], 0, v[148:149]
	v_cvt_pk_bf16_f32 v124, v124, v125
	v_cvt_pk_bf16_f32 v125, v126, v127
	v_cvt_pk_bf16_f32 v126, v120, v121
	v_cvt_pk_bf16_f32 v127, v122, v123
	global_store_dwordx4 v[138:139], v[124:127], off
	v_cvt_pk_bf16_f32 v112, v112, v113
	v_cvt_pk_bf16_f32 v113, v114, v115
	v_cvt_pk_bf16_f32 v114, v104, v105
	v_or_b32_e32 v104, 16, v140
	v_ashrrev_i32_e32 v105, 31, v104
	v_lshlrev_b64 v[104:105], 12, v[104:105]
	v_lshl_add_u64 v[104:105], s[8:9], 0, v[104:105]
	v_cvt_pk_bf16_f32 v115, v106, v107
	global_store_dwordx4 v[138:139], v[112:115], off offset:256
	s_mov_b64 s[16:17], 0x90000
	s_nop 0
	v_lshl_add_u64 v[112:113], v[104:105], 0, v[148:149]
	v_cvt_pk_bf16_f32 v104, v116, v117
	v_cvt_pk_bf16_f32 v105, v118, v119
	v_cvt_pk_bf16_f32 v106, v108, v109
	v_cvt_pk_bf16_f32 v107, v110, v111
	global_store_dwordx4 v[112:113], v[104:107], off
	v_cvt_pk_bf16_f32 v96, v96, v97
	v_cvt_pk_bf16_f32 v97, v98, v99
	v_cvt_pk_bf16_f32 v98, v88, v89
	v_or_b32_e32 v88, 32, v140
	v_ashrrev_i32_e32 v89, 31, v88
	v_lshlrev_b64 v[88:89], 12, v[88:89]
	v_lshl_add_u64 v[88:89], s[8:9], 0, v[88:89]
	v_cvt_pk_bf16_f32 v99, v90, v91
	global_store_dwordx4 v[112:113], v[96:99], off offset:256
	s_nop 1
	v_lshl_add_u64 v[96:97], v[88:89], 0, v[148:149]
	v_cvt_pk_bf16_f32 v88, v100, v101
	v_cvt_pk_bf16_f32 v89, v102, v103
	v_cvt_pk_bf16_f32 v90, v92, v93
	v_cvt_pk_bf16_f32 v91, v94, v95
	global_store_dwordx4 v[96:97], v[88:91], off
	v_cvt_pk_bf16_f32 v80, v80, v81
	v_cvt_pk_bf16_f32 v81, v82, v83
	v_cvt_pk_bf16_f32 v82, v72, v73
	v_or_b32_e32 v72, 48, v140
	v_ashrrev_i32_e32 v73, 31, v72
	v_lshlrev_b64 v[72:73], 12, v[72:73]
	v_lshl_add_u64 v[72:73], s[8:9], 0, v[72:73]
	v_cvt_pk_bf16_f32 v83, v74, v75
	global_store_dwordx4 v[96:97], v[80:83], off offset:256
	s_nop 1
	v_lshl_add_u64 v[80:81], v[72:73], 0, v[148:149]
	v_cvt_pk_bf16_f32 v72, v84, v85
	v_cvt_pk_bf16_f32 v73, v86, v87
	v_cvt_pk_bf16_f32 v74, v76, v77
	v_cvt_pk_bf16_f32 v75, v78, v79
	global_store_dwordx4 v[80:81], v[72:75], off
	v_cvt_pk_bf16_f32 v68, v68, v69
	v_cvt_pk_bf16_f32 v69, v70, v71
	v_cvt_pk_bf16_f32 v70, v64, v65
	v_cvt_pk_bf16_f32 v71, v66, v67
	global_store_dwordx4 v[80:81], v[68:71], off offset:256
	v_cvt_pk_bf16_f32 v60, v60, v61
	v_cvt_pk_bf16_f32 v61, v62, v63
	v_cvt_pk_bf16_f32 v62, v56, v57
	v_add_co_u32_e32 v56, vcc, s85, v138
	v_lshl_add_u64 v[64:65], v[138:139], 0, s[24:25]
	s_nop 0
	v_addc_co_u32_e32 v57, vcc, 0, v139, vcc
	v_cvt_pk_bf16_f32 v63, v58, v59
	global_store_dwordx4 v[56:57], v[60:63], off
	v_cvt_pk_bf16_f32 v48, v48, v49
	v_cvt_pk_bf16_f32 v49, v50, v51
	v_cvt_pk_bf16_f32 v50, v40, v41
	v_cvt_pk_bf16_f32 v51, v42, v43
	global_store_dwordx4 v[64:65], v[48:51], off offset:256
	v_cvt_pk_bf16_f32 v40, v52, v53
	v_cvt_pk_bf16_f32 v41, v54, v55
	v_cvt_pk_bf16_f32 v42, v44, v45
	v_cvt_pk_bf16_f32 v43, v46, v47
	s_nop 1
	v_lshl_add_u64 v[48:49], v[138:139], 0, s[16:17]
	s_mov_b32 s16, 0x90000
	v_add_co_u32_e32 v44, vcc, s16, v138
	s_mov_b64 s[16:17], 0xa0000
	s_nop 0
	v_addc_co_u32_e32 v45, vcc, 0, v139, vcc
	global_store_dwordx4 v[44:45], v[40:43], off
	v_cvt_pk_bf16_f32 v32, v32, v33
	v_cvt_pk_bf16_f32 v33, v34, v35
	v_cvt_pk_bf16_f32 v34, v24, v25
	v_cvt_pk_bf16_f32 v35, v26, v27
	global_store_dwordx4 v[48:49], v[32:35], off offset:256
	v_cvt_pk_bf16_f32 v24, v36, v37
	v_cvt_pk_bf16_f32 v25, v38, v39
	v_cvt_pk_bf16_f32 v26, v28, v29
	v_cvt_pk_bf16_f32 v27, v30, v31
	s_nop 1
	v_lshl_add_u64 v[32:33], v[138:139], 0, s[16:17]
	s_mov_b32 s16, 0xa0000
	v_add_co_u32_e32 v28, vcc, s16, v138
	s_mov_b64 s[16:17], -1
	s_nop 0
	v_addc_co_u32_e32 v29, vcc, 0, v139, vcc
	global_store_dwordx4 v[28:29], v[24:27], off
	v_cvt_pk_bf16_f32 v16, v16, v17
	v_cvt_pk_bf16_f32 v17, v18, v19
	v_cvt_pk_bf16_f32 v18, v8, v9
	v_cvt_pk_bf16_f32 v19, v10, v11
	global_store_dwordx4 v[32:33], v[16:19], off offset:256
	v_cvt_pk_bf16_f32 v8, v20, v21
	v_cvt_pk_bf16_f32 v9, v22, v23
	v_cvt_pk_bf16_f32 v10, v12, v13
	v_add_co_u32_e32 v12, vcc, s81, v138
	s_nop 0
	v_lshl_add_u64 v[16:17], v[138:139], 0, s[54:55]
	v_addc_co_u32_e32 v13, vcc, 0, v139, vcc
	s_andn2_b64 vcc, exec, s[40:41]
	v_cvt_pk_bf16_f32 v11, v14, v15
	global_store_dwordx4 v[12:13], v[8:11], off
	v_cvt_pk_bf16_f32 v4, v4, v5
	v_cvt_pk_bf16_f32 v5, v6, v7
	v_cvt_pk_bf16_f32 v6, v0, v1
	v_cvt_pk_bf16_f32 v7, v2, v3
	global_store_dwordx4 v[16:17], v[4:7], off offset:256
	s_cbranch_vccnz .LBB0_694
	s_andn2_b64 vcc, exec, s[6:7]
	s_cbranch_vccnz .LBB0_693
	s_barrier
	s_branch .LBB0_693
